# v43 minus the redundant post-barrier lgkmcnt(0) waits at the head of each MFMA cluster in the six GEMM main loops
# baseline (speedup 1.0000x reference)
; #define PG8_STAGE(bufoff, gbase, voff) do { _Pragma("unroll") for (int _i = 0; _i < 2; ++_i) \
;         __builtin_amdgcn_global_load_lds((const unsigned*)((const char*)(gbase) + (voff)[_i]), (LAS unsigned*)(lds + (bufoff) + ldsw + _i * 8192), 16, 0, 0); } while (0)
; #define PG8_LDA(dst, b, h) do { _Pragma("unroll") for (int m = 0; m < 4; ++m) _Pragma("unroll") for (int k = 0; k < 2; ++k) dst[m][k] = *(const LAS bf16x8*)(lds + PG8_SA(b, h) + aoff + m * 2048 + k * 1024); } while (0)
; #define PG8_LDB(dst, b, h) do { _Pragma("unroll") for (int n = 0; n < 2; ++n) _Pragma("unroll") for (int k = 0; k < 2; ++k) dst[n][k] = *(const LAS bf16x8*)(lds + PG8_SB(b, h) + boff + n * 2048 + k * 1024); } while (0)
; #define PG8_MMA(ai, bj, At, Bt) do { __builtin_amdgcn_s_setprio(1); _Pragma("unroll") for (int m = 0; m < 4; ++m) _Pragma("unroll") for (int n = 0; n < 2; ++n) _Pragma("unroll") for (int k = 0; k < 2; ++k) \
;         acc[ai][bj][m][n] = __builtin_amdgcn_mfma_f32_16x16x32_bf16(Bt[n][k], At[m][k], acc[ai][bj][m][n], 0, 0, 0); __builtin_amdgcn_s_setprio(0); } while (0)
; #define PG8_WAIT_V(n) asm volatile("s_waitcnt vmcnt(" #n ")" ::: "memory")
; #define PG8_WAIT_L(n) asm volatile("s_waitcnt lgkmcnt(" #n ")" ::: "memory")
; #define PG8_BAR __builtin_amdgcn_s_barrier()
; #define PG8_SCHED __builtin_amdgcn_sched_barrier(0)
; template <class Epi, class Sched>
; __device__ __forceinline__ void gemm_phase(LAS unsigned char* lds, const int K, const Sched& S, const Epi& E) {
;     ...
;         for (int t = 0; t < nt; t += 2) {
;             const bool last = (t == nt - 2);
;             const char* a1 = cA + (size_t)(t + 1) * kstep;
;             const char* a2 = last ? nA : cA + (size_t)(t + 2) * kstep; const char* b2 = last ? nB : cB + (size_t)(t + 2) * kstep;
;             const char* a3 = a2 + kstep; const char* b3 = b2 + kstep;
;             PG8_LDB(B0, 0, 0); PG8_LDB(B1, 0, 1); PG8_SCHED; PG8_LDA(At, 0, 0); PG8_STAGE(PG8_SA(1, 1), a1 + hstep, voffA);
;             PG8_WAIT_V(8); PG8_WAIT_L(0); PG8_BAR; PG8_MMA(0, 0, At, B0); PG8_MMA(0, 1, At, B1); PG8_BAR; PG8_SCHED;
;             PG8_LDA(At, 0, 1); PG8_STAGE(PG8_SB(0, 0), b2, voffB); PG8_STAGE(PG8_SB(0, 1), b2 + hstep, voffB); PG8_STAGE(PG8_SA(0, 0), a2, voffA);
;             PG8_WAIT_V(8); PG8_WAIT_L(0); PG8_BAR; PG8_MMA(1, 0, At, B0); PG8_MMA(1, 1, At, B1); PG8_BAR; PG8_SCHED;
.LBB0_485:
	ds_read_b128 v[140:143], v147
	ds_read_b128 v[150:153], v147 offset:1024
	ds_read_b128 v[154:157], v147 offset:2048
	ds_read_b128 v[158:161], v147 offset:3072
	ds_read_b128 v[162:165], v148
	ds_read_b128 v[170:173], v148 offset:1024
	ds_read_b128 v[174:177], v148 offset:2048
	ds_read_b128 v[178:181], v148 offset:3072
	s_add_u32 s19, s34, 0xfff80080
	s_addc_u32 s38, s35, -1
	s_cmp_eq_u32 s17, 28
	s_cselect_b32 s41, s23, s38
	s_cselect_b32 s40, s22, s19
	s_cselect_b32 s39, s25, s9
	s_cselect_b32 s38, s24, s8
	s_mov_b32 m0, s50
	v_lshl_add_u64 v[166:167], s[34:35], 0, v[136:137]
	ds_read_b128 v[182:185], v149
	ds_read_b128 v[186:189], v149 offset:1024
	ds_read_b128 v[190:193], v149 offset:2048
	ds_read_b128 v[194:197], v149 offset:3072
	ds_read_b128 v[198:201], v149 offset:4096
	ds_read_b128 v[202:205], v149 offset:5120
	ds_read_b128 v[206:209], v149 offset:6144
	ds_read_b128 v[210:213], v149 offset:7168
	global_load_lds_dwordx4 v[166:167], off
	v_lshl_add_u64 v[166:167], s[34:35], 0, v[138:139]
	s_mov_b32 m0, s51
	s_nop 0
	global_load_lds_dwordx4 v[166:167], off
	s_waitcnt vmcnt(8)
	s_waitcnt lgkmcnt(0)
	s_barrier
	s_setprio 1
	v_mfma_f32_16x16x32_bf16 v[124:127], v[140:143], v[182:185], v[124:127]
	v_mfma_f32_16x16x32_bf16 v[120:123], v[154:157], v[182:185], v[120:123]
	v_mfma_f32_16x16x32_bf16 v[108:111], v[140:143], v[190:193], v[108:111]
	v_mfma_f32_16x16x32_bf16 v[104:107], v[154:157], v[190:193], v[104:107]
	v_mfma_f32_16x16x32_bf16 v[92:95], v[140:143], v[198:201], v[92:95]
	v_mfma_f32_16x16x32_bf16 v[88:91], v[154:157], v[198:201], v[88:91]
	v_mfma_f32_16x16x32_bf16 v[76:79], v[140:143], v[206:209], v[76:79]
	v_mfma_f32_16x16x32_bf16 v[72:75], v[154:157], v[206:209], v[72:75]
	v_mfma_f32_16x16x32_bf16 v[124:127], v[150:153], v[186:189], v[124:127]
	v_mfma_f32_16x16x32_bf16 v[120:123], v[158:161], v[186:189], v[120:123]
	v_mfma_f32_16x16x32_bf16 v[108:111], v[150:153], v[194:197], v[108:111]
	v_mfma_f32_16x16x32_bf16 v[104:107], v[158:161], v[194:197], v[104:107]
	v_mfma_f32_16x16x32_bf16 v[92:95], v[150:153], v[202:205], v[92:95]
	v_mfma_f32_16x16x32_bf16 v[88:91], v[158:161], v[202:205], v[88:91]
	v_mfma_f32_16x16x32_bf16 v[76:79], v[150:153], v[210:213], v[76:79]
	v_mfma_f32_16x16x32_bf16 v[72:75], v[158:161], v[210:213], v[72:75]
	v_mfma_f32_16x16x32_bf16 v[116:119], v[162:165], v[182:185], v[116:119]
	v_mfma_f32_16x16x32_bf16 v[112:115], v[174:177], v[182:185], v[112:115]
	v_mfma_f32_16x16x32_bf16 v[100:103], v[162:165], v[190:193], v[100:103]
	v_mfma_f32_16x16x32_bf16 v[96:99], v[174:177], v[190:193], v[96:99]
	v_mfma_f32_16x16x32_bf16 v[84:87], v[162:165], v[198:201], v[84:87]
	v_mfma_f32_16x16x32_bf16 v[80:83], v[174:177], v[198:201], v[80:83]
	v_mfma_f32_16x16x32_bf16 v[68:71], v[162:165], v[206:209], v[68:71]
	v_mfma_f32_16x16x32_bf16 v[64:67], v[174:177], v[206:209], v[64:67]
	v_mfma_f32_16x16x32_bf16 v[116:119], v[170:173], v[186:189], v[116:119]
	v_mfma_f32_16x16x32_bf16 v[112:115], v[178:181], v[186:189], v[112:115]
	v_mfma_f32_16x16x32_bf16 v[100:103], v[170:173], v[194:197], v[100:103]
	v_mfma_f32_16x16x32_bf16 v[96:99], v[178:181], v[194:197], v[96:99]
	v_mfma_f32_16x16x32_bf16 v[84:87], v[170:173], v[202:205], v[84:87]
	v_mfma_f32_16x16x32_bf16 v[80:83], v[178:181], v[202:205], v[80:83]
	v_mfma_f32_16x16x32_bf16 v[68:71], v[170:173], v[210:213], v[68:71]
	v_mfma_f32_16x16x32_bf16 v[64:67], v[178:181], v[210:213], v[64:67]
	s_setprio 0
	s_barrier
	s_mov_b32 m0, s68
	v_lshl_add_u64 v[166:167], s[38:39], 0, v[130:131]
	ds_read_b128 v[182:185], v149 offset:16384
	ds_read_b128 v[186:189], v149 offset:17408
	ds_read_b128 v[190:193], v149 offset:18432
	ds_read_b128 v[194:197], v149 offset:19456
	ds_read_b128 v[198:201], v149 offset:20480
	ds_read_b128 v[202:205], v149 offset:21504
	ds_read_b128 v[206:209], v149 offset:22528
	ds_read_b128 v[210:213], v149 offset:23552
	global_load_lds_dwordx4 v[166:167], off
	s_add_i32 m0, s68, 0x2000
	s_add_u32 s70, s38, 0x80000
	v_lshl_add_u64 v[214:215], s[38:39], 0, v[134:135]
	s_addc_u32 s71, s39, 0
	s_add_i32 s19, s48, s36
	global_load_lds_dwordx4 v[214:215], off
	v_lshl_add_u64 v[216:217], s[70:71], 0, v[130:131]
	s_mov_b32 m0, s19
	v_lshl_add_u64 v[218:219], s[40:41], 0, v[132:133]
	global_load_lds_dwordx4 v[216:217], off
	v_lshl_add_u64 v[216:217], s[70:71], 0, v[134:135]
	s_add_i32 m0, s19, 0x2000
	s_nop 0
	global_load_lds_dwordx4 v[216:217], off
	v_lshl_add_u64 v[216:217], s[40:41], 0, v[128:129]
	s_mov_b32 m0, s31
	s_nop 0
	global_load_lds_dwordx4 v[216:217], off
	s_mov_b32 m0, s42
	s_nop 0
	global_load_lds_dwordx4 v[218:219], off
	s_waitcnt vmcnt(8)
	s_waitcnt lgkmcnt(0)
	s_barrier
; #define PG8_STAGE(bufoff, gbase, voff) do { _Pragma("unroll") for (int _i = 0; _i < 2; ++_i) \
;         __builtin_amdgcn_global_load_lds((const unsigned*)((const char*)(gbase) + (voff)[_i]), (LAS unsigned*)(lds + (bufoff) + ldsw + _i * 8192), 16, 0, 0); } while (0)
; #define PG8_LDA(dst, b, h) do { _Pragma("unroll") for (int m = 0; m < 4; ++m) _Pragma("unroll") for (int k = 0; k < 2; ++k) dst[m][k] = *(const LAS bf16x8*)(lds + PG8_SA(b, h) + aoff + m * 2048 + k * 1024); } while (0)
; #define PG8_LDB(dst, b, h) do { _Pragma("unroll") for (int n = 0; n < 2; ++n) _Pragma("unroll") for (int k = 0; k < 2; ++k) dst[n][k] = *(const LAS bf16x8*)(lds + PG8_SB(b, h) + boff + n * 2048 + k * 1024); } while (0)
; #define PG8_MMA(ai, bj, At, Bt) do { __builtin_amdgcn_s_setprio(1); _Pragma("unroll") for (int m = 0; m < 4; ++m) _Pragma("unroll") for (int n = 0; n < 2; ++n) _Pragma("unroll") for (int k = 0; k < 2; ++k) \
;         acc[ai][bj][m][n] = __builtin_amdgcn_mfma_f32_16x16x32_bf16(Bt[n][k], At[m][k], acc[ai][bj][m][n], 0, 0, 0); __builtin_amdgcn_s_setprio(0); } while (0)
; #define PG8_WAIT_V(n) asm volatile("s_waitcnt vmcnt(" #n ")" ::: "memory")
; #define PG8_WAIT_L(n) asm volatile("s_waitcnt lgkmcnt(" #n ")" ::: "memory")
; #define PG8_BAR __builtin_amdgcn_s_barrier()
; #define PG8_SCHED __builtin_amdgcn_sched_barrier(0)
; template <class Epi, class Sched>
; __device__ __forceinline__ void gemm_phase(LAS unsigned char* lds, const int K, const Sched& S, const Epi& E) {
;     ...
;             PG8_WAIT_V(8); PG8_WAIT_L(0); PG8_BAR; PG8_MMA(1, 0, At, B0); PG8_MMA(1, 1, At, B1); PG8_BAR; PG8_SCHED;
;             PG8_LDB(B0, 1, 0); PG8_LDB(B1, 1, 1); PG8_SCHED; PG8_LDA(At, 1, 0); PG8_STAGE(PG8_SA(0, 1), a2 + hstep, voffA);
;             PG8_WAIT_V(8); PG8_WAIT_L(0); PG8_BAR; PG8_MMA(0, 0, At, B0); PG8_MMA(0, 1, At, B1); PG8_BAR; PG8_SCHED;
	s_setprio 1
	v_mfma_f32_16x16x32_bf16 v[60:63], v[140:143], v[182:185], v[60:63]
	v_mfma_f32_16x16x32_bf16 v[56:59], v[154:157], v[182:185], v[56:59]
	v_mfma_f32_16x16x32_bf16 v[44:47], v[140:143], v[190:193], v[44:47]
	v_mfma_f32_16x16x32_bf16 v[40:43], v[154:157], v[190:193], v[40:43]
	v_mfma_f32_16x16x32_bf16 v[28:31], v[140:143], v[198:201], v[28:31]
	v_mfma_f32_16x16x32_bf16 v[24:27], v[154:157], v[198:201], v[24:27]
	v_mfma_f32_16x16x32_bf16 v[12:15], v[140:143], v[206:209], v[12:15]
	v_mfma_f32_16x16x32_bf16 v[8:11], v[154:157], v[206:209], v[8:11]
	v_mfma_f32_16x16x32_bf16 v[60:63], v[150:153], v[186:189], v[60:63]
	v_mfma_f32_16x16x32_bf16 v[56:59], v[158:161], v[186:189], v[56:59]
	v_mfma_f32_16x16x32_bf16 v[44:47], v[150:153], v[194:197], v[44:47]
	v_mfma_f32_16x16x32_bf16 v[40:43], v[158:161], v[194:197], v[40:43]
	v_mfma_f32_16x16x32_bf16 v[28:31], v[150:153], v[202:205], v[28:31]
	v_mfma_f32_16x16x32_bf16 v[24:27], v[158:161], v[202:205], v[24:27]
	v_mfma_f32_16x16x32_bf16 v[12:15], v[150:153], v[210:213], v[12:15]
	v_mfma_f32_16x16x32_bf16 v[8:11], v[158:161], v[210:213], v[8:11]
	v_mfma_f32_16x16x32_bf16 v[52:55], v[162:165], v[182:185], v[52:55]
	v_mfma_f32_16x16x32_bf16 v[48:51], v[174:177], v[182:185], v[48:51]
	v_mfma_f32_16x16x32_bf16 v[36:39], v[162:165], v[190:193], v[36:39]
	v_mfma_f32_16x16x32_bf16 v[32:35], v[174:177], v[190:193], v[32:35]
	v_mfma_f32_16x16x32_bf16 v[20:23], v[162:165], v[198:201], v[20:23]
	v_mfma_f32_16x16x32_bf16 v[16:19], v[174:177], v[198:201], v[16:19]
	v_mfma_f32_16x16x32_bf16 v[4:7], v[162:165], v[206:209], v[4:7]
	v_mfma_f32_16x16x32_bf16 v[0:3], v[174:177], v[206:209], v[0:3]
	v_mfma_f32_16x16x32_bf16 v[52:55], v[170:173], v[186:189], v[52:55]
	v_mfma_f32_16x16x32_bf16 v[48:51], v[178:181], v[186:189], v[48:51]
	v_mfma_f32_16x16x32_bf16 v[36:39], v[170:173], v[194:197], v[36:39]
	v_mfma_f32_16x16x32_bf16 v[32:35], v[178:181], v[194:197], v[32:35]
	v_mfma_f32_16x16x32_bf16 v[20:23], v[170:173], v[202:205], v[20:23]
	v_mfma_f32_16x16x32_bf16 v[16:19], v[178:181], v[202:205], v[16:19]
	v_mfma_f32_16x16x32_bf16 v[4:7], v[170:173], v[210:213], v[4:7]
	v_mfma_f32_16x16x32_bf16 v[0:3], v[178:181], v[210:213], v[0:3]
	s_setprio 0
	s_barrier
	s_add_i32 s19, 0, 0x18000
	s_add_i32 s70, 0, 0x1c000
	v_add_u32_e32 v158, s19, v145
	v_add_u32_e32 v169, s70, v145
	ds_read_b128 v[140:143], v158
	ds_read_b128 v[150:153], v158 offset:1024
	ds_read_b128 v[154:157], v158 offset:2048
	ds_read_b128 v[158:161], v158 offset:3072
	ds_read_b128 v[162:165], v169
	ds_read_b128 v[170:173], v169 offset:1024
	ds_read_b128 v[174:177], v169 offset:2048
	ds_read_b128 v[178:181], v169 offset:3072
	s_add_u32 s40, s40, 0x80000
	s_addc_u32 s41, s41, 0
	s_mov_b32 m0, s43
	v_lshl_add_u64 v[220:221], s[40:41], 0, v[128:129]
	ds_read_b128 v[182:185], v149 offset:32768
	ds_read_b128 v[186:189], v149 offset:33792
	ds_read_b128 v[190:193], v149 offset:34816
	ds_read_b128 v[194:197], v149 offset:35840
	ds_read_b128 v[198:201], v149 offset:36864
	ds_read_b128 v[202:205], v149 offset:37888
	ds_read_b128 v[206:209], v149 offset:38912
	ds_read_b128 v[210:213], v149 offset:39936
	global_load_lds_dwordx4 v[220:221], off
	v_lshl_add_u64 v[220:221], s[40:41], 0, v[132:133]
	s_mov_b32 m0, s44
	s_nop 0
	global_load_lds_dwordx4 v[220:221], off
	s_waitcnt vmcnt(8)
	s_waitcnt lgkmcnt(0)
	s_barrier
	s_setprio 1
	v_mfma_f32_16x16x32_bf16 v[124:127], v[140:143], v[182:185], v[124:127]
	v_mfma_f32_16x16x32_bf16 v[120:123], v[154:157], v[182:185], v[120:123]
	v_mfma_f32_16x16x32_bf16 v[108:111], v[140:143], v[190:193], v[108:111]
	v_mfma_f32_16x16x32_bf16 v[104:107], v[154:157], v[190:193], v[104:107]
	v_mfma_f32_16x16x32_bf16 v[92:95], v[140:143], v[198:201], v[92:95]
	v_mfma_f32_16x16x32_bf16 v[88:91], v[154:157], v[198:201], v[88:91]
	v_mfma_f32_16x16x32_bf16 v[76:79], v[140:143], v[206:209], v[76:79]
	v_mfma_f32_16x16x32_bf16 v[72:75], v[154:157], v[206:209], v[72:75]
	v_mfma_f32_16x16x32_bf16 v[124:127], v[150:153], v[186:189], v[124:127]
	v_mfma_f32_16x16x32_bf16 v[120:123], v[158:161], v[186:189], v[120:123]
	v_mfma_f32_16x16x32_bf16 v[108:111], v[150:153], v[194:197], v[108:111]
	v_mfma_f32_16x16x32_bf16 v[104:107], v[158:161], v[194:197], v[104:107]
	v_mfma_f32_16x16x32_bf16 v[92:95], v[150:153], v[202:205], v[92:95]
	v_mfma_f32_16x16x32_bf16 v[88:91], v[158:161], v[202:205], v[88:91]
	v_mfma_f32_16x16x32_bf16 v[76:79], v[150:153], v[210:213], v[76:79]
	v_mfma_f32_16x16x32_bf16 v[72:75], v[158:161], v[210:213], v[72:75]
	v_mfma_f32_16x16x32_bf16 v[116:119], v[162:165], v[182:185], v[116:119]
	v_mfma_f32_16x16x32_bf16 v[112:115], v[174:177], v[182:185], v[112:115]
	v_mfma_f32_16x16x32_bf16 v[100:103], v[162:165], v[190:193], v[100:103]
	v_mfma_f32_16x16x32_bf16 v[96:99], v[174:177], v[190:193], v[96:99]
	v_mfma_f32_16x16x32_bf16 v[84:87], v[162:165], v[198:201], v[84:87]
	v_mfma_f32_16x16x32_bf16 v[80:83], v[174:177], v[198:201], v[80:83]
	v_mfma_f32_16x16x32_bf16 v[68:71], v[162:165], v[206:209], v[68:71]
	v_mfma_f32_16x16x32_bf16 v[64:67], v[174:177], v[206:209], v[64:67]
	v_mfma_f32_16x16x32_bf16 v[116:119], v[170:173], v[186:189], v[116:119]
	v_mfma_f32_16x16x32_bf16 v[112:115], v[178:181], v[186:189], v[112:115]
	v_mfma_f32_16x16x32_bf16 v[100:103], v[170:173], v[194:197], v[100:103]
	v_mfma_f32_16x16x32_bf16 v[96:99], v[178:181], v[194:197], v[96:99]
	v_mfma_f32_16x16x32_bf16 v[84:87], v[170:173], v[202:205], v[84:87]
	v_mfma_f32_16x16x32_bf16 v[80:83], v[178:181], v[202:205], v[80:83]
	v_mfma_f32_16x16x32_bf16 v[68:71], v[170:173], v[210:213], v[68:71]
	v_mfma_f32_16x16x32_bf16 v[64:67], v[178:181], v[210:213], v[64:67]
	s_setprio 0
	s_barrier
; #define PG8_STAGE(bufoff, gbase, voff) do { _Pragma("unroll") for (int _i = 0; _i < 2; ++_i) \
;         __builtin_amdgcn_global_load_lds((const unsigned*)((const char*)(gbase) + (voff)[_i]), (LAS unsigned*)(lds + (bufoff) + ldsw + _i * 8192), 16, 0, 0); } while (0)
; #define PG8_LDA(dst, b, h) do { _Pragma("unroll") for (int m = 0; m < 4; ++m) _Pragma("unroll") for (int k = 0; k < 2; ++k) dst[m][k] = *(const LAS bf16x8*)(lds + PG8_SA(b, h) + aoff + m * 2048 + k * 1024); } while (0)
; #define PG8_MMA(ai, bj, At, Bt) do { __builtin_amdgcn_s_setprio(1); _Pragma("unroll") for (int m = 0; m < 4; ++m) _Pragma("unroll") for (int n = 0; n < 2; ++n) _Pragma("unroll") for (int k = 0; k < 2; ++k) \
;         acc[ai][bj][m][n] = __builtin_amdgcn_mfma_f32_16x16x32_bf16(Bt[n][k], At[m][k], acc[ai][bj][m][n], 0, 0, 0); __builtin_amdgcn_s_setprio(0); } while (0)
; #define PG8_WAIT_V(n) asm volatile("s_waitcnt vmcnt(" #n ")" ::: "memory")
; #define PG8_WAIT_L(n) asm volatile("s_waitcnt lgkmcnt(" #n ")" ::: "memory")
; #define PG8_BAR __builtin_amdgcn_s_barrier()
; #define PG8_SCHED __builtin_amdgcn_sched_barrier(0)
; template <class Epi, class Sched>
; __device__ __forceinline__ void gemm_phase(LAS unsigned char* lds, const int K, const Sched& S, const Epi& E) {
;     ...
;             PG8_LDA(At, 1, 1); PG8_STAGE(PG8_SB(1, 0), b3, voffB); PG8_STAGE(PG8_SB(1, 1), b3 + hstep, voffB); PG8_STAGE(PG8_SA(1, 0), a3, voffA);
;             PG8_WAIT_V(8); PG8_WAIT_L(0); PG8_BAR; PG8_MMA(1, 0, At, B0); PG8_MMA(1, 1, At, B1); PG8_BAR; PG8_SCHED;
;         }
;         if (wr == 0) PG8_BAR;
	s_add_i32 s19, s19, s36
	v_lshl_add_u64 v[166:167], v[166:167], 0, s[10:11]
	s_mov_b32 m0, s19
	ds_read_b128 v[182:185], v149 offset:49152
	ds_read_b128 v[186:189], v149 offset:50176
	ds_read_b128 v[190:193], v149 offset:51200
	ds_read_b128 v[194:197], v149 offset:52224
	ds_read_b128 v[198:201], v149 offset:53248
	ds_read_b128 v[202:205], v149 offset:54272
	ds_read_b128 v[206:209], v149 offset:55296
	ds_read_b128 v[210:213], v149 offset:56320
	global_load_lds_dwordx4 v[166:167], off
	s_add_i32 m0, s19, 0x2000
	s_add_u32 s38, s38, 0x80080
	v_lshl_add_u64 v[166:167], v[214:215], 0, s[10:11]
	s_addc_u32 s39, s39, 0
	s_add_i32 s19, s70, s36
	global_load_lds_dwordx4 v[166:167], off
	v_lshl_add_u64 v[166:167], s[38:39], 0, v[130:131]
	s_mov_b32 m0, s19
	s_nop 0
	global_load_lds_dwordx4 v[166:167], off
	v_lshl_add_u64 v[166:167], s[38:39], 0, v[134:135]
	s_add_i32 m0, s19, 0x2000
	s_nop 0
	global_load_lds_dwordx4 v[166:167], off
	v_lshl_add_u64 v[166:167], v[216:217], 0, s[10:11]
	s_mov_b32 m0, s46
	s_nop 0
	global_load_lds_dwordx4 v[166:167], off
	v_lshl_add_u64 v[166:167], v[218:219], 0, s[10:11]
	s_mov_b32 m0, s47
	s_nop 0
	global_load_lds_dwordx4 v[166:167], off
	s_waitcnt vmcnt(8)
	s_waitcnt lgkmcnt(0)
	s_barrier
	s_setprio 1
	v_mfma_f32_16x16x32_bf16 v[60:63], v[140:143], v[182:185], v[60:63]
	v_mfma_f32_16x16x32_bf16 v[56:59], v[154:157], v[182:185], v[56:59]
	v_mfma_f32_16x16x32_bf16 v[44:47], v[140:143], v[190:193], v[44:47]
	v_mfma_f32_16x16x32_bf16 v[40:43], v[154:157], v[190:193], v[40:43]
	v_mfma_f32_16x16x32_bf16 v[28:31], v[140:143], v[198:201], v[28:31]
	v_mfma_f32_16x16x32_bf16 v[24:27], v[154:157], v[198:201], v[24:27]
	v_mfma_f32_16x16x32_bf16 v[12:15], v[140:143], v[206:209], v[12:15]
	v_mfma_f32_16x16x32_bf16 v[8:11], v[154:157], v[206:209], v[8:11]
	v_mfma_f32_16x16x32_bf16 v[60:63], v[150:153], v[186:189], v[60:63]
	v_mfma_f32_16x16x32_bf16 v[56:59], v[158:161], v[186:189], v[56:59]
	v_mfma_f32_16x16x32_bf16 v[44:47], v[150:153], v[194:197], v[44:47]
	v_mfma_f32_16x16x32_bf16 v[40:43], v[158:161], v[194:197], v[40:43]
	v_mfma_f32_16x16x32_bf16 v[28:31], v[150:153], v[202:205], v[28:31]
	v_mfma_f32_16x16x32_bf16 v[24:27], v[158:161], v[202:205], v[24:27]
	v_mfma_f32_16x16x32_bf16 v[12:15], v[150:153], v[210:213], v[12:15]
	v_mfma_f32_16x16x32_bf16 v[8:11], v[158:161], v[210:213], v[8:11]
	v_mfma_f32_16x16x32_bf16 v[52:55], v[162:165], v[182:185], v[52:55]
	v_mfma_f32_16x16x32_bf16 v[48:51], v[174:177], v[182:185], v[48:51]
	v_mfma_f32_16x16x32_bf16 v[36:39], v[162:165], v[190:193], v[36:39]
	v_mfma_f32_16x16x32_bf16 v[32:35], v[174:177], v[190:193], v[32:35]
	v_mfma_f32_16x16x32_bf16 v[20:23], v[162:165], v[198:201], v[20:23]
	v_mfma_f32_16x16x32_bf16 v[16:19], v[174:177], v[198:201], v[16:19]
	v_mfma_f32_16x16x32_bf16 v[4:7], v[162:165], v[206:209], v[4:7]
	v_mfma_f32_16x16x32_bf16 v[0:3], v[174:177], v[206:209], v[0:3]
	v_mfma_f32_16x16x32_bf16 v[52:55], v[170:173], v[186:189], v[52:55]
	v_mfma_f32_16x16x32_bf16 v[48:51], v[178:181], v[186:189], v[48:51]
	v_mfma_f32_16x16x32_bf16 v[36:39], v[170:173], v[194:197], v[36:39]
	v_mfma_f32_16x16x32_bf16 v[32:35], v[178:181], v[194:197], v[32:35]
	v_mfma_f32_16x16x32_bf16 v[20:23], v[170:173], v[202:205], v[20:23]
	v_mfma_f32_16x16x32_bf16 v[16:19], v[178:181], v[202:205], v[16:19]
	v_mfma_f32_16x16x32_bf16 v[4:7], v[170:173], v[210:213], v[4:7]
	v_mfma_f32_16x16x32_bf16 v[0:3], v[178:181], v[210:213], v[0:3]
	s_setprio 0
	s_barrier
	s_add_i32 s17, s17, 2
	s_add_u32 s34, s34, 0x100
	s_addc_u32 s35, s35, 0
	s_add_u32 s8, s8, 0x100
	s_addc_u32 s9, s9, 0
	s_cmp_gt_u32 s17, 29
	s_cbranch_scc0 .LBB0_485
	s_and_b64 vcc, exec, s[14:15]
	s_cbranch_vccz .LBB0_488
	s_barrier

; #define PG8_STAGE(bufoff, gbase, voff) do { _Pragma("unroll") for (int _i = 0; _i < 2; ++_i) \
;         __builtin_amdgcn_global_load_lds((const unsigned*)((const char*)(gbase) + (voff)[_i]), (LAS unsigned*)(lds + (bufoff) + ldsw + _i * 8192), 16, 0, 0); } while (0)
; #define PG8_LDA(dst, b, h) do { _Pragma("unroll") for (int m = 0; m < 4; ++m) _Pragma("unroll") for (int k = 0; k < 2; ++k) dst[m][k] = *(const LAS bf16x8*)(lds + PG8_SA(b, h) + aoff + m * 2048 + k * 1024); } while (0)
; #define PG8_LDB(dst, b, h) do { _Pragma("unroll") for (int n = 0; n < 2; ++n) _Pragma("unroll") for (int k = 0; k < 2; ++k) dst[n][k] = *(const LAS bf16x8*)(lds + PG8_SB(b, h) + boff + n * 2048 + k * 1024); } while (0)
; #define PG8_MMA(ai, bj, At, Bt) do { __builtin_amdgcn_s_setprio(1); _Pragma("unroll") for (int m = 0; m < 4; ++m) _Pragma("unroll") for (int n = 0; n < 2; ++n) _Pragma("unroll") for (int k = 0; k < 2; ++k) \
;         acc[ai][bj][m][n] = __builtin_amdgcn_mfma_f32_16x16x32_bf16(Bt[n][k], At[m][k], acc[ai][bj][m][n], 0, 0, 0); __builtin_amdgcn_s_setprio(0); } while (0)
; #define PG8_WAIT_V(n) asm volatile("s_waitcnt vmcnt(" #n ")" ::: "memory")
; #define PG8_WAIT_L(n) asm volatile("s_waitcnt lgkmcnt(" #n ")" ::: "memory")
; #define PG8_BAR __builtin_amdgcn_s_barrier()
; #define PG8_SCHED __builtin_amdgcn_sched_barrier(0)
; template <class Epi, class Sched>
; __device__ __forceinline__ void gemm_phase(LAS unsigned char* lds, const int K, const Sched& S, const Epi& E) {
;     ...
;         for (int t = 0; t < nt; t += 2) {
;             const bool last = (t == nt - 2);
;             const char* a1 = cA + (size_t)(t + 1) * kstep;
;             const char* a2 = last ? nA : cA + (size_t)(t + 2) * kstep; const char* b2 = last ? nB : cB + (size_t)(t + 2) * kstep;
;             const char* a3 = a2 + kstep; const char* b3 = b2 + kstep;
;             PG8_LDB(B0, 0, 0); PG8_LDB(B1, 0, 1); PG8_SCHED; PG8_LDA(At, 0, 0); PG8_STAGE(PG8_SA(1, 1), a1 + hstep, voffA);
;             PG8_WAIT_V(8); PG8_WAIT_L(0); PG8_BAR; PG8_MMA(0, 0, At, B0); PG8_MMA(0, 1, At, B1); PG8_BAR; PG8_SCHED;
;             PG8_LDA(At, 0, 1); PG8_STAGE(PG8_SB(0, 0), b2, voffB); PG8_STAGE(PG8_SB(0, 1), b2 + hstep, voffB); PG8_STAGE(PG8_SA(0, 0), a2, voffA);
;             PG8_WAIT_V(8); PG8_WAIT_L(0); PG8_BAR; PG8_MMA(1, 0, At, B0); PG8_MMA(1, 1, At, B1); PG8_BAR; PG8_SCHED;
.LBB0_565:
	ds_read_b128 v[140:143], v147
	ds_read_b128 v[152:155], v147 offset:1024
	ds_read_b128 v[156:159], v147 offset:2048
	ds_read_b128 v[160:163], v147 offset:3072
	ds_read_b128 v[164:167], v148
	ds_read_b128 v[170:173], v148 offset:1024
	ds_read_b128 v[174:177], v148 offset:2048
	ds_read_b128 v[178:181], v148 offset:3072
	s_add_u32 s24, s22, 0xffea0080
	s_addc_u32 s25, s23, -1
	s_cmpk_eq_i32 s71, 0x54
	s_cselect_b32 s31, s17, s25
	s_cselect_b32 s30, s16, s24
	s_cselect_b32 s25, s19, s9
	s_cselect_b32 s24, s18, s8
	s_mov_b32 m0, s46
	v_lshl_add_u64 v[214:215], s[22:23], 0, v[136:137]
	ds_read_b128 v[182:185], v149
	ds_read_b128 v[186:189], v149 offset:1024
	ds_read_b128 v[190:193], v149 offset:2048
	ds_read_b128 v[194:197], v149 offset:3072
	ds_read_b128 v[198:201], v149 offset:4096
	ds_read_b128 v[202:205], v149 offset:5120
	ds_read_b128 v[206:209], v149 offset:6144
	ds_read_b128 v[210:213], v149 offset:7168
	global_load_lds_dwordx4 v[214:215], off
	v_lshl_add_u64 v[214:215], s[22:23], 0, v[138:139]
	s_mov_b32 m0, s47
	s_nop 0
	global_load_lds_dwordx4 v[214:215], off
	s_waitcnt vmcnt(8)
	s_waitcnt lgkmcnt(0)
	s_barrier
	s_setprio 1
	v_mfma_f32_16x16x32_bf16 v[124:127], v[140:143], v[182:185], v[124:127]
	v_mfma_f32_16x16x32_bf16 v[120:123], v[156:159], v[182:185], v[120:123]
	v_mfma_f32_16x16x32_bf16 v[108:111], v[140:143], v[190:193], v[108:111]
	v_mfma_f32_16x16x32_bf16 v[104:107], v[156:159], v[190:193], v[104:107]
	v_mfma_f32_16x16x32_bf16 v[92:95], v[140:143], v[198:201], v[92:95]
	v_mfma_f32_16x16x32_bf16 v[88:91], v[156:159], v[198:201], v[88:91]
	v_mfma_f32_16x16x32_bf16 v[76:79], v[140:143], v[206:209], v[76:79]
	v_mfma_f32_16x16x32_bf16 v[72:75], v[156:159], v[206:209], v[72:75]
	v_mfma_f32_16x16x32_bf16 v[124:127], v[152:155], v[186:189], v[124:127]
	v_mfma_f32_16x16x32_bf16 v[120:123], v[160:163], v[186:189], v[120:123]
	v_mfma_f32_16x16x32_bf16 v[108:111], v[152:155], v[194:197], v[108:111]
	v_mfma_f32_16x16x32_bf16 v[104:107], v[160:163], v[194:197], v[104:107]
	v_mfma_f32_16x16x32_bf16 v[92:95], v[152:155], v[202:205], v[92:95]
	v_mfma_f32_16x16x32_bf16 v[88:91], v[160:163], v[202:205], v[88:91]
	v_mfma_f32_16x16x32_bf16 v[76:79], v[152:155], v[210:213], v[76:79]
	v_mfma_f32_16x16x32_bf16 v[72:75], v[160:163], v[210:213], v[72:75]
	v_mfma_f32_16x16x32_bf16 v[116:119], v[164:167], v[182:185], v[116:119]
	v_mfma_f32_16x16x32_bf16 v[112:115], v[174:177], v[182:185], v[112:115]
	v_mfma_f32_16x16x32_bf16 v[100:103], v[164:167], v[190:193], v[100:103]
	v_mfma_f32_16x16x32_bf16 v[96:99], v[174:177], v[190:193], v[96:99]
	v_mfma_f32_16x16x32_bf16 v[84:87], v[164:167], v[198:201], v[84:87]
	v_mfma_f32_16x16x32_bf16 v[80:83], v[174:177], v[198:201], v[80:83]
	v_mfma_f32_16x16x32_bf16 v[68:71], v[164:167], v[206:209], v[68:71]
	v_mfma_f32_16x16x32_bf16 v[64:67], v[174:177], v[206:209], v[64:67]
	v_mfma_f32_16x16x32_bf16 v[116:119], v[170:173], v[186:189], v[116:119]
	v_mfma_f32_16x16x32_bf16 v[112:115], v[178:181], v[186:189], v[112:115]
	v_mfma_f32_16x16x32_bf16 v[100:103], v[170:173], v[194:197], v[100:103]
	v_mfma_f32_16x16x32_bf16 v[96:99], v[178:181], v[194:197], v[96:99]
	v_mfma_f32_16x16x32_bf16 v[84:87], v[170:173], v[202:205], v[84:87]
	v_mfma_f32_16x16x32_bf16 v[80:83], v[178:181], v[202:205], v[80:83]
	v_mfma_f32_16x16x32_bf16 v[68:71], v[170:173], v[210:213], v[68:71]
	v_mfma_f32_16x16x32_bf16 v[64:67], v[178:181], v[210:213], v[64:67]
	s_setprio 0
	s_barrier
	s_mov_b32 m0, s48
	v_lshl_add_u64 v[214:215], s[24:25], 0, v[130:131]
	s_add_u32 s72, s24, 0x160000
	ds_read_b128 v[182:185], v149 offset:16384
	ds_read_b128 v[186:189], v149 offset:17408
	ds_read_b128 v[190:193], v149 offset:18432
	ds_read_b128 v[194:197], v149 offset:19456
	ds_read_b128 v[198:201], v149 offset:20480
	ds_read_b128 v[202:205], v149 offset:21504
	ds_read_b128 v[206:209], v149 offset:22528
	ds_read_b128 v[210:213], v149 offset:23552
	global_load_lds_dwordx4 v[214:215], off
	v_lshl_add_u64 v[216:217], s[24:25], 0, v[134:135]
	s_mov_b32 m0, s49
	s_addc_u32 s73, s25, 0
	global_load_lds_dwordx4 v[216:217], off
	v_lshl_add_u64 v[218:219], s[72:73], 0, v[130:131]
	s_mov_b32 m0, s50
	v_lshl_add_u64 v[220:221], s[30:31], 0, v[132:133]
	global_load_lds_dwordx4 v[218:219], off
	v_lshl_add_u64 v[218:219], s[72:73], 0, v[134:135]
	s_add_i32 m0, s50, 0x2000
	s_nop 0
	global_load_lds_dwordx4 v[218:219], off
	v_lshl_add_u64 v[218:219], s[30:31], 0, v[128:129]
	s_mov_b32 m0, s37
	s_nop 0
	global_load_lds_dwordx4 v[218:219], off
	s_mov_b32 m0, s38
	s_nop 0
	global_load_lds_dwordx4 v[220:221], off
	s_waitcnt vmcnt(8)
	s_waitcnt lgkmcnt(0)
	s_barrier
; #define PG8_STAGE(bufoff, gbase, voff) do { _Pragma("unroll") for (int _i = 0; _i < 2; ++_i) \
;         __builtin_amdgcn_global_load_lds((const unsigned*)((const char*)(gbase) + (voff)[_i]), (LAS unsigned*)(lds + (bufoff) + ldsw + _i * 8192), 16, 0, 0); } while (0)
; #define PG8_LDA(dst, b, h) do { _Pragma("unroll") for (int m = 0; m < 4; ++m) _Pragma("unroll") for (int k = 0; k < 2; ++k) dst[m][k] = *(const LAS bf16x8*)(lds + PG8_SA(b, h) + aoff + m * 2048 + k * 1024); } while (0)
; #define PG8_LDB(dst, b, h) do { _Pragma("unroll") for (int n = 0; n < 2; ++n) _Pragma("unroll") for (int k = 0; k < 2; ++k) dst[n][k] = *(const LAS bf16x8*)(lds + PG8_SB(b, h) + boff + n * 2048 + k * 1024); } while (0)
; #define PG8_MMA(ai, bj, At, Bt) do { __builtin_amdgcn_s_setprio(1); _Pragma("unroll") for (int m = 0; m < 4; ++m) _Pragma("unroll") for (int n = 0; n < 2; ++n) _Pragma("unroll") for (int k = 0; k < 2; ++k) \
;         acc[ai][bj][m][n] = __builtin_amdgcn_mfma_f32_16x16x32_bf16(Bt[n][k], At[m][k], acc[ai][bj][m][n], 0, 0, 0); __builtin_amdgcn_s_setprio(0); } while (0)
; #define PG8_WAIT_V(n) asm volatile("s_waitcnt vmcnt(" #n ")" ::: "memory")
; #define PG8_WAIT_L(n) asm volatile("s_waitcnt lgkmcnt(" #n ")" ::: "memory")
; #define PG8_BAR __builtin_amdgcn_s_barrier()
; #define PG8_SCHED __builtin_amdgcn_sched_barrier(0)
; template <class Epi, class Sched>
; __device__ __forceinline__ void gemm_phase(LAS unsigned char* lds, const int K, const Sched& S, const Epi& E) {
;     ...
;             PG8_WAIT_V(8); PG8_WAIT_L(0); PG8_BAR; PG8_MMA(1, 0, At, B0); PG8_MMA(1, 1, At, B1); PG8_BAR; PG8_SCHED;
;             PG8_LDB(B0, 1, 0); PG8_LDB(B1, 1, 1); PG8_SCHED; PG8_LDA(At, 1, 0); PG8_STAGE(PG8_SA(0, 1), a2 + hstep, voffA);
;             PG8_WAIT_V(8); PG8_WAIT_L(0); PG8_BAR; PG8_MMA(0, 0, At, B0); PG8_MMA(0, 1, At, B1); PG8_BAR; PG8_SCHED;
	s_setprio 1
	v_mfma_f32_16x16x32_bf16 v[60:63], v[140:143], v[182:185], v[60:63]
	v_mfma_f32_16x16x32_bf16 v[56:59], v[156:159], v[182:185], v[56:59]
	v_mfma_f32_16x16x32_bf16 v[44:47], v[140:143], v[190:193], v[44:47]
	v_mfma_f32_16x16x32_bf16 v[40:43], v[156:159], v[190:193], v[40:43]
	v_mfma_f32_16x16x32_bf16 v[28:31], v[140:143], v[198:201], v[28:31]
	v_mfma_f32_16x16x32_bf16 v[24:27], v[156:159], v[198:201], v[24:27]
	v_mfma_f32_16x16x32_bf16 v[12:15], v[140:143], v[206:209], v[12:15]
	v_mfma_f32_16x16x32_bf16 v[8:11], v[156:159], v[206:209], v[8:11]
	v_mfma_f32_16x16x32_bf16 v[60:63], v[152:155], v[186:189], v[60:63]
	v_mfma_f32_16x16x32_bf16 v[56:59], v[160:163], v[186:189], v[56:59]
	v_mfma_f32_16x16x32_bf16 v[44:47], v[152:155], v[194:197], v[44:47]
	v_mfma_f32_16x16x32_bf16 v[40:43], v[160:163], v[194:197], v[40:43]
	v_mfma_f32_16x16x32_bf16 v[28:31], v[152:155], v[202:205], v[28:31]
	v_mfma_f32_16x16x32_bf16 v[24:27], v[160:163], v[202:205], v[24:27]
	v_mfma_f32_16x16x32_bf16 v[12:15], v[152:155], v[210:213], v[12:15]
	v_mfma_f32_16x16x32_bf16 v[8:11], v[160:163], v[210:213], v[8:11]
	v_mfma_f32_16x16x32_bf16 v[52:55], v[164:167], v[182:185], v[52:55]
	v_mfma_f32_16x16x32_bf16 v[48:51], v[174:177], v[182:185], v[48:51]
	v_mfma_f32_16x16x32_bf16 v[36:39], v[164:167], v[190:193], v[36:39]
	v_mfma_f32_16x16x32_bf16 v[32:35], v[174:177], v[190:193], v[32:35]
	v_mfma_f32_16x16x32_bf16 v[20:23], v[164:167], v[198:201], v[20:23]
	v_mfma_f32_16x16x32_bf16 v[16:19], v[174:177], v[198:201], v[16:19]
	v_mfma_f32_16x16x32_bf16 v[4:7], v[164:167], v[206:209], v[4:7]
	v_mfma_f32_16x16x32_bf16 v[0:3], v[174:177], v[206:209], v[0:3]
	v_mfma_f32_16x16x32_bf16 v[52:55], v[170:173], v[186:189], v[52:55]
	v_mfma_f32_16x16x32_bf16 v[48:51], v[178:181], v[186:189], v[48:51]
	v_mfma_f32_16x16x32_bf16 v[36:39], v[170:173], v[194:197], v[36:39]
	v_mfma_f32_16x16x32_bf16 v[32:35], v[178:181], v[194:197], v[32:35]
	v_mfma_f32_16x16x32_bf16 v[20:23], v[170:173], v[202:205], v[20:23]
	v_mfma_f32_16x16x32_bf16 v[16:19], v[178:181], v[202:205], v[16:19]
	v_mfma_f32_16x16x32_bf16 v[4:7], v[170:173], v[210:213], v[4:7]
	v_mfma_f32_16x16x32_bf16 v[0:3], v[178:181], v[210:213], v[0:3]
	s_setprio 0
	s_barrier
	s_add_i32 s72, 0, 0x18000
	v_add_u32_e32 v151, s72, v146
	s_add_i32 s73, 0, 0x1c000
	ds_read_b128 v[140:143], v151
	ds_read_b128 v[152:155], v151 offset:1024
	ds_read_b128 v[156:159], v151 offset:2048
	ds_read_b128 v[160:163], v151 offset:3072
	v_add_u32_e32 v151, s73, v146
	ds_read_b128 v[164:167], v151
	ds_read_b128 v[170:173], v151 offset:1024
	ds_read_b128 v[174:177], v151 offset:2048
	ds_read_b128 v[178:181], v151 offset:3072
	s_add_u32 s30, s30, 0x160000
	s_addc_u32 s31, s31, 0
	s_mov_b32 m0, s39
	v_lshl_add_u64 v[224:225], s[30:31], 0, v[128:129]
	ds_read_b128 v[182:185], v149 offset:32768
	ds_read_b128 v[186:189], v149 offset:33792
	ds_read_b128 v[190:193], v149 offset:34816
	ds_read_b128 v[194:197], v149 offset:35840
	ds_read_b128 v[198:201], v149 offset:36864
	ds_read_b128 v[202:205], v149 offset:37888
	ds_read_b128 v[206:209], v149 offset:38912
	ds_read_b128 v[210:213], v149 offset:39936
	global_load_lds_dwordx4 v[224:225], off
	v_lshl_add_u64 v[224:225], s[30:31], 0, v[132:133]
	s_mov_b32 m0, s40
	s_nop 0
	global_load_lds_dwordx4 v[224:225], off
	s_waitcnt vmcnt(8)
	s_waitcnt lgkmcnt(0)
	s_barrier
	s_setprio 1
	v_mfma_f32_16x16x32_bf16 v[124:127], v[140:143], v[182:185], v[124:127]
	v_mfma_f32_16x16x32_bf16 v[120:123], v[156:159], v[182:185], v[120:123]
	v_mfma_f32_16x16x32_bf16 v[108:111], v[140:143], v[190:193], v[108:111]
	v_mfma_f32_16x16x32_bf16 v[104:107], v[156:159], v[190:193], v[104:107]
	v_mfma_f32_16x16x32_bf16 v[92:95], v[140:143], v[198:201], v[92:95]
	v_mfma_f32_16x16x32_bf16 v[88:91], v[156:159], v[198:201], v[88:91]
	v_mfma_f32_16x16x32_bf16 v[76:79], v[140:143], v[206:209], v[76:79]
	v_mfma_f32_16x16x32_bf16 v[72:75], v[156:159], v[206:209], v[72:75]
	v_mfma_f32_16x16x32_bf16 v[124:127], v[152:155], v[186:189], v[124:127]
	v_mfma_f32_16x16x32_bf16 v[120:123], v[160:163], v[186:189], v[120:123]
	v_mfma_f32_16x16x32_bf16 v[108:111], v[152:155], v[194:197], v[108:111]
	v_mfma_f32_16x16x32_bf16 v[104:107], v[160:163], v[194:197], v[104:107]
	v_mfma_f32_16x16x32_bf16 v[92:95], v[152:155], v[202:205], v[92:95]
	v_mfma_f32_16x16x32_bf16 v[88:91], v[160:163], v[202:205], v[88:91]
	v_mfma_f32_16x16x32_bf16 v[76:79], v[152:155], v[210:213], v[76:79]
	v_mfma_f32_16x16x32_bf16 v[72:75], v[160:163], v[210:213], v[72:75]
	v_mfma_f32_16x16x32_bf16 v[116:119], v[164:167], v[182:185], v[116:119]
	v_mfma_f32_16x16x32_bf16 v[112:115], v[174:177], v[182:185], v[112:115]
	v_mfma_f32_16x16x32_bf16 v[100:103], v[164:167], v[190:193], v[100:103]
	v_mfma_f32_16x16x32_bf16 v[96:99], v[174:177], v[190:193], v[96:99]
	v_mfma_f32_16x16x32_bf16 v[84:87], v[164:167], v[198:201], v[84:87]
	v_mfma_f32_16x16x32_bf16 v[80:83], v[174:177], v[198:201], v[80:83]
	v_mfma_f32_16x16x32_bf16 v[68:71], v[164:167], v[206:209], v[68:71]
	v_mfma_f32_16x16x32_bf16 v[64:67], v[174:177], v[206:209], v[64:67]
	v_mfma_f32_16x16x32_bf16 v[116:119], v[170:173], v[186:189], v[116:119]
	v_mfma_f32_16x16x32_bf16 v[112:115], v[178:181], v[186:189], v[112:115]
	v_mfma_f32_16x16x32_bf16 v[100:103], v[170:173], v[194:197], v[100:103]
	v_mfma_f32_16x16x32_bf16 v[96:99], v[178:181], v[194:197], v[96:99]
	v_mfma_f32_16x16x32_bf16 v[84:87], v[170:173], v[202:205], v[84:87]
	v_mfma_f32_16x16x32_bf16 v[80:83], v[178:181], v[202:205], v[80:83]
	v_mfma_f32_16x16x32_bf16 v[68:71], v[170:173], v[210:213], v[68:71]
	v_mfma_f32_16x16x32_bf16 v[64:67], v[178:181], v[210:213], v[64:67]
	s_setprio 0
	s_barrier
; #define PG8_STAGE(bufoff, gbase, voff) do { _Pragma("unroll") for (int _i = 0; _i < 2; ++_i) \
;         __builtin_amdgcn_global_load_lds((const unsigned*)((const char*)(gbase) + (voff)[_i]), (LAS unsigned*)(lds + (bufoff) + ldsw + _i * 8192), 16, 0, 0); } while (0)
; #define PG8_LDA(dst, b, h) do { _Pragma("unroll") for (int m = 0; m < 4; ++m) _Pragma("unroll") for (int k = 0; k < 2; ++k) dst[m][k] = *(const LAS bf16x8*)(lds + PG8_SA(b, h) + aoff + m * 2048 + k * 1024); } while (0)
; #define PG8_MMA(ai, bj, At, Bt) do { __builtin_amdgcn_s_setprio(1); _Pragma("unroll") for (int m = 0; m < 4; ++m) _Pragma("unroll") for (int n = 0; n < 2; ++n) _Pragma("unroll") for (int k = 0; k < 2; ++k) \
;         acc[ai][bj][m][n] = __builtin_amdgcn_mfma_f32_16x16x32_bf16(Bt[n][k], At[m][k], acc[ai][bj][m][n], 0, 0, 0); __builtin_amdgcn_s_setprio(0); } while (0)
; #define PG8_WAIT_V(n) asm volatile("s_waitcnt vmcnt(" #n ")" ::: "memory")
; #define PG8_WAIT_L(n) asm volatile("s_waitcnt lgkmcnt(" #n ")" ::: "memory")
; #define PG8_BAR __builtin_amdgcn_s_barrier()
; #define PG8_SCHED __builtin_amdgcn_sched_barrier(0)
; template <class Epi, class Sched>
; __device__ __forceinline__ void gemm_phase(LAS unsigned char* lds, const int K, const Sched& S, const Epi& E) {
;     ...
;             PG8_LDA(At, 1, 1); PG8_STAGE(PG8_SB(1, 0), b3, voffB); PG8_STAGE(PG8_SB(1, 1), b3 + hstep, voffB); PG8_STAGE(PG8_SA(1, 0), a3, voffA);
;             PG8_WAIT_V(8); PG8_WAIT_L(0); PG8_BAR; PG8_MMA(1, 0, At, B0); PG8_MMA(1, 1, At, B1); PG8_BAR; PG8_SCHED;
;         }
;         if (wr == 0) PG8_BAR;
	s_add_i32 s30, s72, s36
	v_lshl_add_u64 v[214:215], v[214:215], 0, s[10:11]
	s_mov_b32 m0, s30
	ds_read_b128 v[182:185], v149 offset:49152
	ds_read_b128 v[186:189], v149 offset:50176
	ds_read_b128 v[190:193], v149 offset:51200
	ds_read_b128 v[194:197], v149 offset:52224
	ds_read_b128 v[198:201], v149 offset:53248
	ds_read_b128 v[202:205], v149 offset:54272
	ds_read_b128 v[206:209], v149 offset:55296
	ds_read_b128 v[210:213], v149 offset:56320
	global_load_lds_dwordx4 v[214:215], off
	s_add_i32 m0, s30, 0x2000
	s_add_u32 s24, s24, 0x160080
	v_lshl_add_u64 v[214:215], v[216:217], 0, s[10:11]
	s_addc_u32 s25, s25, 0
	s_add_i32 s30, s73, s36
	global_load_lds_dwordx4 v[214:215], off
	v_lshl_add_u64 v[214:215], s[24:25], 0, v[130:131]
	s_mov_b32 m0, s30
	s_nop 0
	global_load_lds_dwordx4 v[214:215], off
	v_lshl_add_u64 v[214:215], s[24:25], 0, v[134:135]
	s_add_i32 m0, s30, 0x2000
	s_nop 0
	global_load_lds_dwordx4 v[214:215], off
	v_lshl_add_u64 v[214:215], v[218:219], 0, s[10:11]
	s_mov_b32 m0, s44
	s_nop 0
	global_load_lds_dwordx4 v[214:215], off
	v_lshl_add_u64 v[214:215], v[220:221], 0, s[10:11]
	s_mov_b32 m0, s45
	s_nop 0
	global_load_lds_dwordx4 v[214:215], off
	s_waitcnt vmcnt(8)
	s_waitcnt lgkmcnt(0)
	s_barrier
	s_setprio 1
	v_mfma_f32_16x16x32_bf16 v[60:63], v[140:143], v[182:185], v[60:63]
	v_mfma_f32_16x16x32_bf16 v[56:59], v[156:159], v[182:185], v[56:59]
	v_mfma_f32_16x16x32_bf16 v[44:47], v[140:143], v[190:193], v[44:47]
	v_mfma_f32_16x16x32_bf16 v[40:43], v[156:159], v[190:193], v[40:43]
	v_mfma_f32_16x16x32_bf16 v[28:31], v[140:143], v[198:201], v[28:31]
	v_mfma_f32_16x16x32_bf16 v[24:27], v[156:159], v[198:201], v[24:27]
	v_mfma_f32_16x16x32_bf16 v[12:15], v[140:143], v[206:209], v[12:15]
	v_mfma_f32_16x16x32_bf16 v[8:11], v[156:159], v[206:209], v[8:11]
	v_mfma_f32_16x16x32_bf16 v[60:63], v[152:155], v[186:189], v[60:63]
	v_mfma_f32_16x16x32_bf16 v[56:59], v[160:163], v[186:189], v[56:59]
	v_mfma_f32_16x16x32_bf16 v[44:47], v[152:155], v[194:197], v[44:47]
	v_mfma_f32_16x16x32_bf16 v[40:43], v[160:163], v[194:197], v[40:43]
	v_mfma_f32_16x16x32_bf16 v[28:31], v[152:155], v[202:205], v[28:31]
	v_mfma_f32_16x16x32_bf16 v[24:27], v[160:163], v[202:205], v[24:27]
	v_mfma_f32_16x16x32_bf16 v[12:15], v[152:155], v[210:213], v[12:15]
	v_mfma_f32_16x16x32_bf16 v[8:11], v[160:163], v[210:213], v[8:11]
	v_mfma_f32_16x16x32_bf16 v[52:55], v[164:167], v[182:185], v[52:55]
	v_mfma_f32_16x16x32_bf16 v[48:51], v[174:177], v[182:185], v[48:51]
	v_mfma_f32_16x16x32_bf16 v[36:39], v[164:167], v[190:193], v[36:39]
	v_mfma_f32_16x16x32_bf16 v[32:35], v[174:177], v[190:193], v[32:35]
	v_mfma_f32_16x16x32_bf16 v[20:23], v[164:167], v[198:201], v[20:23]
	v_mfma_f32_16x16x32_bf16 v[16:19], v[174:177], v[198:201], v[16:19]
	v_mfma_f32_16x16x32_bf16 v[4:7], v[164:167], v[206:209], v[4:7]
	v_mfma_f32_16x16x32_bf16 v[0:3], v[174:177], v[206:209], v[0:3]
	v_mfma_f32_16x16x32_bf16 v[52:55], v[170:173], v[186:189], v[52:55]
	v_mfma_f32_16x16x32_bf16 v[48:51], v[178:181], v[186:189], v[48:51]
	v_mfma_f32_16x16x32_bf16 v[36:39], v[170:173], v[194:197], v[36:39]
	v_mfma_f32_16x16x32_bf16 v[32:35], v[178:181], v[194:197], v[32:35]
	v_mfma_f32_16x16x32_bf16 v[20:23], v[170:173], v[202:205], v[20:23]
	v_mfma_f32_16x16x32_bf16 v[16:19], v[178:181], v[202:205], v[16:19]
	v_mfma_f32_16x16x32_bf16 v[4:7], v[170:173], v[210:213], v[4:7]
	v_mfma_f32_16x16x32_bf16 v[0:3], v[178:181], v[210:213], v[0:3]
	s_setprio 0
	s_barrier
	s_add_i32 s71, s71, 2
	s_add_u32 s22, s22, 0x100
	s_addc_u32 s23, s23, 0
	s_add_u32 s8, s8, 0x100
	s_addc_u32 s9, s9, 0
	s_cmpk_gt_u32 s71, 0x55
	s_cbranch_scc0 .LBB0_565
	s_and_b64 vcc, exec, s[14:15]
	s_cbranch_vccz .LBB0_568
	s_barrier

; #define PG8_STAGE(bufoff, gbase, voff) do { _Pragma("unroll") for (int _i = 0; _i < 2; ++_i) \
;         __builtin_amdgcn_global_load_lds((const unsigned*)((const char*)(gbase) + (voff)[_i]), (LAS unsigned*)(lds + (bufoff) + ldsw + _i * 8192), 16, 0, 0); } while (0)
; #define PG8_LDA(dst, b, h) do { _Pragma("unroll") for (int m = 0; m < 4; ++m) _Pragma("unroll") for (int k = 0; k < 2; ++k) dst[m][k] = *(const LAS bf16x8*)(lds + PG8_SA(b, h) + aoff + m * 2048 + k * 1024); } while (0)
; #define PG8_LDB(dst, b, h) do { _Pragma("unroll") for (int n = 0; n < 2; ++n) _Pragma("unroll") for (int k = 0; k < 2; ++k) dst[n][k] = *(const LAS bf16x8*)(lds + PG8_SB(b, h) + boff + n * 2048 + k * 1024); } while (0)
; #define PG8_MMA(ai, bj, At, Bt) do { __builtin_amdgcn_s_setprio(1); _Pragma("unroll") for (int m = 0; m < 4; ++m) _Pragma("unroll") for (int n = 0; n < 2; ++n) _Pragma("unroll") for (int k = 0; k < 2; ++k) \
;         acc[ai][bj][m][n] = __builtin_amdgcn_mfma_f32_16x16x32_bf16(Bt[n][k], At[m][k], acc[ai][bj][m][n], 0, 0, 0); __builtin_amdgcn_s_setprio(0); } while (0)
; #define PG8_WAIT_V(n) asm volatile("s_waitcnt vmcnt(" #n ")" ::: "memory")
; #define PG8_WAIT_L(n) asm volatile("s_waitcnt lgkmcnt(" #n ")" ::: "memory")
; #define PG8_BAR __builtin_amdgcn_s_barrier()
; #define PG8_SCHED __builtin_amdgcn_sched_barrier(0)
; template <class Epi, class Sched>
; __device__ __forceinline__ void gemm_phase(LAS unsigned char* lds, const int K, const Sched& S, const Epi& E) {
;     ...
;         for (int t = 0; t < nt; t += 2) {
;             const bool last = (t == nt - 2);
;             const char* a1 = cA + (size_t)(t + 1) * kstep;
;             const char* a2 = last ? nA : cA + (size_t)(t + 2) * kstep; const char* b2 = last ? nB : cB + (size_t)(t + 2) * kstep;
;             const char* a3 = a2 + kstep; const char* b3 = b2 + kstep;
;             PG8_LDB(B0, 0, 0); PG8_LDB(B1, 0, 1); PG8_SCHED; PG8_LDA(At, 0, 0); PG8_STAGE(PG8_SA(1, 1), a1 + hstep, voffA);
;             PG8_WAIT_V(8); PG8_WAIT_L(0); PG8_BAR; PG8_MMA(0, 0, At, B0); PG8_MMA(0, 1, At, B1); PG8_BAR; PG8_SCHED;
;             PG8_LDA(At, 0, 1); PG8_STAGE(PG8_SB(0, 0), b2, voffB); PG8_STAGE(PG8_SB(0, 1), b2 + hstep, voffB); PG8_STAGE(PG8_SA(0, 0), a2, voffA);
;             PG8_WAIT_V(8); PG8_WAIT_L(0); PG8_BAR; PG8_MMA(1, 0, At, B0); PG8_MMA(1, 1, At, B1); PG8_BAR; PG8_SCHED;
.LBB0_661:
	ds_read_b128 v[0:3], v227
	ds_read_b128 v[4:7], v227 offset:1024
	ds_read_b128 v[8:11], v227 offset:2048
	ds_read_b128 v[12:15], v227 offset:3072
	ds_read_b128 v[16:19], v228
	ds_read_b128 v[20:23], v228 offset:1024
	ds_read_b128 v[152:155], v228 offset:2048
	ds_read_b128 v[156:159], v228 offset:3072
	s_add_u32 s36, s6, 0xfff80080
	s_addc_u32 s37, s7, -1
	s_cmp_eq_u32 s9, 28
	s_cselect_b32 s75, s69, s37
	s_cselect_b32 s74, s68, s36
	s_cselect_b32 s73, s71, s8
	s_cselect_b32 s72, s70, s1
	v_lshl_add_u64 v[210:211], s[6:7], 0, v[180:181]
	s_add_i32 m0, s47, 0xc000
	ds_read_b128 v[160:163], v229
	ds_read_b128 v[164:167], v229 offset:1024
	ds_read_b128 v[186:189], v229 offset:2048
	ds_read_b128 v[190:193], v229 offset:3072
	ds_read_b128 v[194:197], v229 offset:4096
	ds_read_b128 v[198:201], v229 offset:5120
	ds_read_b128 v[202:205], v229 offset:6144
	ds_read_b128 v[206:209], v229 offset:7168
	global_load_lds_dwordx4 v[210:211], off
	v_lshl_add_u64 v[210:211], s[6:7], 0, v[182:183]
	s_add_i32 m0, s47, 0xe000
	s_nop 0
	global_load_lds_dwordx4 v[210:211], off
	s_waitcnt vmcnt(8)
	s_waitcnt lgkmcnt(0)
	s_barrier
	s_setprio 1
	v_mfma_f32_16x16x32_bf16 v[148:151], v[0:3], v[160:163], v[148:151]
	v_mfma_f32_16x16x32_bf16 v[144:147], v[8:11], v[160:163], v[144:147]
	v_mfma_f32_16x16x32_bf16 v[132:135], v[0:3], v[186:189], v[132:135]
	v_mfma_f32_16x16x32_bf16 v[128:131], v[8:11], v[186:189], v[128:131]
	v_mfma_f32_16x16x32_bf16 v[116:119], v[0:3], v[194:197], v[116:119]
	v_mfma_f32_16x16x32_bf16 v[112:115], v[8:11], v[194:197], v[112:115]
	v_mfma_f32_16x16x32_bf16 v[100:103], v[0:3], v[202:205], v[100:103]
	v_mfma_f32_16x16x32_bf16 v[96:99], v[8:11], v[202:205], v[96:99]
	v_mfma_f32_16x16x32_bf16 v[148:151], v[4:7], v[164:167], v[148:151]
	v_mfma_f32_16x16x32_bf16 v[144:147], v[12:15], v[164:167], v[144:147]
	v_mfma_f32_16x16x32_bf16 v[132:135], v[4:7], v[190:193], v[132:135]
	v_mfma_f32_16x16x32_bf16 v[128:131], v[12:15], v[190:193], v[128:131]
	v_mfma_f32_16x16x32_bf16 v[116:119], v[4:7], v[198:201], v[116:119]
	v_mfma_f32_16x16x32_bf16 v[112:115], v[12:15], v[198:201], v[112:115]
	v_mfma_f32_16x16x32_bf16 v[100:103], v[4:7], v[206:209], v[100:103]
	v_mfma_f32_16x16x32_bf16 v[96:99], v[12:15], v[206:209], v[96:99]
	v_mfma_f32_16x16x32_bf16 v[140:143], v[16:19], v[160:163], v[140:143]
	v_mfma_f32_16x16x32_bf16 v[136:139], v[152:155], v[160:163], v[136:139]
	v_mfma_f32_16x16x32_bf16 v[124:127], v[16:19], v[186:189], v[124:127]
	v_mfma_f32_16x16x32_bf16 v[120:123], v[152:155], v[186:189], v[120:123]
	v_mfma_f32_16x16x32_bf16 v[108:111], v[16:19], v[194:197], v[108:111]
	v_mfma_f32_16x16x32_bf16 v[104:107], v[152:155], v[194:197], v[104:107]
	v_mfma_f32_16x16x32_bf16 v[92:95], v[16:19], v[202:205], v[92:95]
	v_mfma_f32_16x16x32_bf16 v[88:91], v[152:155], v[202:205], v[88:91]
	v_mfma_f32_16x16x32_bf16 v[140:143], v[20:23], v[164:167], v[140:143]
	v_mfma_f32_16x16x32_bf16 v[136:139], v[156:159], v[164:167], v[136:139]
	v_mfma_f32_16x16x32_bf16 v[124:127], v[20:23], v[190:193], v[124:127]
	v_mfma_f32_16x16x32_bf16 v[120:123], v[156:159], v[190:193], v[120:123]
	v_mfma_f32_16x16x32_bf16 v[108:111], v[20:23], v[198:201], v[108:111]
	v_mfma_f32_16x16x32_bf16 v[104:107], v[156:159], v[198:201], v[104:107]
	v_mfma_f32_16x16x32_bf16 v[92:95], v[20:23], v[206:209], v[92:95]
	v_mfma_f32_16x16x32_bf16 v[88:91], v[156:159], v[206:209], v[88:91]
	s_setprio 0
	s_barrier
	s_add_i32 s36, s92, s45
	v_lshl_add_u64 v[218:219], s[72:73], 0, v[172:173]
	s_mov_b32 m0, s36
	ds_read_b128 v[160:163], v229 offset:16384
	ds_read_b128 v[164:167], v229 offset:17408
	ds_read_b128 v[186:189], v229 offset:18432
	ds_read_b128 v[190:193], v229 offset:19456
	ds_read_b128 v[194:197], v229 offset:20480
	ds_read_b128 v[198:201], v229 offset:21504
	ds_read_b128 v[202:205], v229 offset:22528
	ds_read_b128 v[206:209], v229 offset:23552
	global_load_lds_dwordx4 v[218:219], off
	s_add_i32 m0, s36, 0x2000
	s_add_u32 s36, s72, 0x80000
	v_lshl_add_u64 v[220:221], s[72:73], 0, v[176:177]
	s_addc_u32 s37, s73, 0
	s_add_i32 s42, s93, s45
	global_load_lds_dwordx4 v[220:221], off
	v_lshl_add_u64 v[210:211], s[36:37], 0, v[172:173]
	s_mov_b32 m0, s42
	v_lshl_add_u64 v[232:233], s[74:75], 0, v[170:171]
	global_load_lds_dwordx4 v[210:211], off
	v_lshl_add_u64 v[210:211], s[36:37], 0, v[176:177]
	s_add_i32 m0, s42, 0x2000
	v_lshl_add_u64 v[234:235], s[74:75], 0, v[174:175]
	global_load_lds_dwordx4 v[210:211], off
	s_mov_b32 m0, s47
	s_nop 0
	global_load_lds_dwordx4 v[232:233], off
	s_mov_b32 m0, s76
	s_nop 0
	global_load_lds_dwordx4 v[234:235], off
	s_waitcnt vmcnt(8)
	s_waitcnt lgkmcnt(0)
	s_barrier
; #define PG8_STAGE(bufoff, gbase, voff) do { _Pragma("unroll") for (int _i = 0; _i < 2; ++_i) \
;         __builtin_amdgcn_global_load_lds((const unsigned*)((const char*)(gbase) + (voff)[_i]), (LAS unsigned*)(lds + (bufoff) + ldsw + _i * 8192), 16, 0, 0); } while (0)
; #define PG8_LDA(dst, b, h) do { _Pragma("unroll") for (int m = 0; m < 4; ++m) _Pragma("unroll") for (int k = 0; k < 2; ++k) dst[m][k] = *(const LAS bf16x8*)(lds + PG8_SA(b, h) + aoff + m * 2048 + k * 1024); } while (0)
; #define PG8_LDB(dst, b, h) do { _Pragma("unroll") for (int n = 0; n < 2; ++n) _Pragma("unroll") for (int k = 0; k < 2; ++k) dst[n][k] = *(const LAS bf16x8*)(lds + PG8_SB(b, h) + boff + n * 2048 + k * 1024); } while (0)
; #define PG8_MMA(ai, bj, At, Bt) do { __builtin_amdgcn_s_setprio(1); _Pragma("unroll") for (int m = 0; m < 4; ++m) _Pragma("unroll") for (int n = 0; n < 2; ++n) _Pragma("unroll") for (int k = 0; k < 2; ++k) \
;         acc[ai][bj][m][n] = __builtin_amdgcn_mfma_f32_16x16x32_bf16(Bt[n][k], At[m][k], acc[ai][bj][m][n], 0, 0, 0); __builtin_amdgcn_s_setprio(0); } while (0)
; #define PG8_WAIT_V(n) asm volatile("s_waitcnt vmcnt(" #n ")" ::: "memory")
; #define PG8_WAIT_L(n) asm volatile("s_waitcnt lgkmcnt(" #n ")" ::: "memory")
; #define PG8_BAR __builtin_amdgcn_s_barrier()
; #define PG8_SCHED __builtin_amdgcn_sched_barrier(0)
; template <class Epi, class Sched>
; __device__ __forceinline__ void gemm_phase(LAS unsigned char* lds, const int K, const Sched& S, const Epi& E) {
;     ...
;             PG8_WAIT_V(8); PG8_WAIT_L(0); PG8_BAR; PG8_MMA(1, 0, At, B0); PG8_MMA(1, 1, At, B1); PG8_BAR; PG8_SCHED;
;             PG8_LDB(B0, 1, 0); PG8_LDB(B1, 1, 1); PG8_SCHED; PG8_LDA(At, 1, 0); PG8_STAGE(PG8_SA(0, 1), a2 + hstep, voffA);
;             PG8_WAIT_V(8); PG8_WAIT_L(0); PG8_BAR; PG8_MMA(0, 0, At, B0); PG8_MMA(0, 1, At, B1); PG8_BAR; PG8_SCHED;
	s_setprio 1
	v_mfma_f32_16x16x32_bf16 v[84:87], v[0:3], v[160:163], v[84:87]
	v_mfma_f32_16x16x32_bf16 v[80:83], v[8:11], v[160:163], v[80:83]
	v_mfma_f32_16x16x32_bf16 v[68:71], v[0:3], v[186:189], v[68:71]
	v_mfma_f32_16x16x32_bf16 v[64:67], v[8:11], v[186:189], v[64:67]
	v_mfma_f32_16x16x32_bf16 v[52:55], v[0:3], v[194:197], v[52:55]
	v_mfma_f32_16x16x32_bf16 v[48:51], v[8:11], v[194:197], v[48:51]
	v_mfma_f32_16x16x32_bf16 v[0:3], v[0:3], v[202:205], v[36:39]
	v_mfma_f32_16x16x32_bf16 v[84:87], v[4:7], v[164:167], v[84:87]
	v_mfma_f32_16x16x32_bf16 v[80:83], v[12:15], v[164:167], v[80:83]
	v_mfma_f32_16x16x32_bf16 v[68:71], v[4:7], v[190:193], v[68:71]
	v_mfma_f32_16x16x32_bf16 v[64:67], v[12:15], v[190:193], v[64:67]
	v_mfma_f32_16x16x32_bf16 v[52:55], v[4:7], v[198:201], v[52:55]
	v_mfma_f32_16x16x32_bf16 v[48:51], v[12:15], v[198:201], v[48:51]
	v_mfma_f32_16x16x32_bf16 v[0:3], v[4:7], v[206:209], v[0:3]
	v_mfma_f32_16x16x32_bf16 v[4:7], v[8:11], v[202:205], v[32:35]
	v_mfma_f32_16x16x32_bf16 v[4:7], v[12:15], v[206:209], v[4:7]
	v_mfma_f32_16x16x32_bf16 v[32:35], v[16:19], v[186:189], v[60:63]
	v_mfma_f32_16x16x32_bf16 v[60:63], v[20:23], v[190:193], v[32:35]
	v_mfma_f32_16x16x32_bf16 v[32:35], v[152:155], v[186:189], v[56:59]
	v_mfma_f32_16x16x32_bf16 v[56:59], v[156:159], v[190:193], v[32:35]
	v_mfma_f32_16x16x32_bf16 v[32:35], v[16:19], v[194:197], v[44:47]
	v_mfma_f32_16x16x32_bf16 v[8:11], v[16:19], v[160:163], v[76:79]
	v_mfma_f32_16x16x32_bf16 v[44:47], v[20:23], v[198:201], v[32:35]
	v_mfma_f32_16x16x32_bf16 v[32:35], v[152:155], v[194:197], v[40:43]
	v_mfma_f32_16x16x32_bf16 v[16:19], v[16:19], v[202:205], v[28:31]
	v_mfma_f32_16x16x32_bf16 v[8:11], v[20:23], v[164:167], v[8:11]
	v_mfma_f32_16x16x32_bf16 v[12:15], v[152:155], v[160:163], v[72:75]
	v_mfma_f32_16x16x32_bf16 v[40:43], v[156:159], v[198:201], v[32:35]
	v_mfma_f32_16x16x32_bf16 v[16:19], v[20:23], v[206:209], v[16:19]
	v_mfma_f32_16x16x32_bf16 v[20:23], v[152:155], v[202:205], v[24:27]
	v_mfma_f32_16x16x32_bf16 v[12:15], v[156:159], v[164:167], v[12:15]
	v_mfma_f32_16x16x32_bf16 v[20:23], v[156:159], v[206:209], v[20:23]
	s_setprio 0
	s_barrier
	s_add_i32 s42, 0, 0x18000
	v_add_u32_e32 v36, s42, v226
	s_add_i32 s43, 0, 0x1c000
	ds_read_b128 v[24:27], v36
	ds_read_b128 v[28:31], v36 offset:1024
	ds_read_b128 v[32:35], v36 offset:2048
	ds_read_b128 v[72:75], v36 offset:3072
	v_add_u32_e32 v36, s43, v226
	ds_read_b128 v[152:155], v36
	ds_read_b128 v[156:159], v36 offset:1024
	ds_read_b128 v[160:163], v36 offset:2048
	ds_read_b128 v[164:167], v36 offset:3072
	s_add_u32 s36, s74, 0x80000
	s_addc_u32 s37, s75, 0
	s_mov_b32 m0, s77
	v_lshl_add_u64 v[210:211], s[36:37], 0, v[170:171]
	ds_read_b128 v[36:39], v229 offset:32768
	ds_read_b128 v[76:79], v229 offset:33792
	ds_read_b128 v[186:189], v229 offset:34816
	ds_read_b128 v[190:193], v229 offset:35840
	ds_read_b128 v[194:197], v229 offset:36864
	ds_read_b128 v[198:201], v229 offset:37888
	ds_read_b128 v[202:205], v229 offset:38912
	ds_read_b128 v[206:209], v229 offset:39936
	global_load_lds_dwordx4 v[210:211], off
	v_lshl_add_u64 v[210:211], s[36:37], 0, v[174:175]
	s_mov_b32 m0, s78
	s_nop 0
	global_load_lds_dwordx4 v[210:211], off
	s_waitcnt vmcnt(8)
	s_waitcnt lgkmcnt(0)
	s_barrier
	s_setprio 1
	v_mfma_f32_16x16x32_bf16 v[148:151], v[24:27], v[36:39], v[148:151]
	v_mfma_f32_16x16x32_bf16 v[144:147], v[32:35], v[36:39], v[144:147]
	v_mfma_f32_16x16x32_bf16 v[132:135], v[24:27], v[186:189], v[132:135]
	v_mfma_f32_16x16x32_bf16 v[128:131], v[32:35], v[186:189], v[128:131]
	v_mfma_f32_16x16x32_bf16 v[116:119], v[24:27], v[194:197], v[116:119]
	v_mfma_f32_16x16x32_bf16 v[112:115], v[32:35], v[194:197], v[112:115]
	v_mfma_f32_16x16x32_bf16 v[100:103], v[24:27], v[202:205], v[100:103]
	v_mfma_f32_16x16x32_bf16 v[96:99], v[32:35], v[202:205], v[96:99]
	v_mfma_f32_16x16x32_bf16 v[148:151], v[28:31], v[76:79], v[148:151]
	v_mfma_f32_16x16x32_bf16 v[144:147], v[72:75], v[76:79], v[144:147]
	v_mfma_f32_16x16x32_bf16 v[132:135], v[28:31], v[190:193], v[132:135]
	v_mfma_f32_16x16x32_bf16 v[128:131], v[72:75], v[190:193], v[128:131]
	v_mfma_f32_16x16x32_bf16 v[116:119], v[28:31], v[198:201], v[116:119]
	v_mfma_f32_16x16x32_bf16 v[112:115], v[72:75], v[198:201], v[112:115]
	v_mfma_f32_16x16x32_bf16 v[100:103], v[28:31], v[206:209], v[100:103]
	v_mfma_f32_16x16x32_bf16 v[96:99], v[72:75], v[206:209], v[96:99]
	v_mfma_f32_16x16x32_bf16 v[140:143], v[152:155], v[36:39], v[140:143]
	v_mfma_f32_16x16x32_bf16 v[36:39], v[160:163], v[36:39], v[136:139]
	v_mfma_f32_16x16x32_bf16 v[136:139], v[164:167], v[76:79], v[36:39]
	v_mfma_f32_16x16x32_bf16 v[36:39], v[152:155], v[186:189], v[124:127]
	v_mfma_f32_16x16x32_bf16 v[124:127], v[156:159], v[190:193], v[36:39]
	v_mfma_f32_16x16x32_bf16 v[36:39], v[160:163], v[186:189], v[120:123]
	v_mfma_f32_16x16x32_bf16 v[120:123], v[164:167], v[190:193], v[36:39]
	v_mfma_f32_16x16x32_bf16 v[36:39], v[152:155], v[194:197], v[108:111]
	v_mfma_f32_16x16x32_bf16 v[108:111], v[156:159], v[198:201], v[36:39]
	v_mfma_f32_16x16x32_bf16 v[36:39], v[160:163], v[194:197], v[104:107]
	v_mfma_f32_16x16x32_bf16 v[104:107], v[164:167], v[198:201], v[36:39]
	v_mfma_f32_16x16x32_bf16 v[36:39], v[152:155], v[202:205], v[92:95]
	v_mfma_f32_16x16x32_bf16 v[92:95], v[156:159], v[206:209], v[36:39]
	v_mfma_f32_16x16x32_bf16 v[36:39], v[160:163], v[202:205], v[88:91]
	v_mfma_f32_16x16x32_bf16 v[140:143], v[156:159], v[76:79], v[140:143]
	v_mfma_f32_16x16x32_bf16 v[88:91], v[164:167], v[206:209], v[36:39]
	s_setprio 0
	s_barrier
; #define PG8_STAGE(bufoff, gbase, voff) do { _Pragma("unroll") for (int _i = 0; _i < 2; ++_i) \
;         __builtin_amdgcn_global_load_lds((const unsigned*)((const char*)(gbase) + (voff)[_i]), (LAS unsigned*)(lds + (bufoff) + ldsw + _i * 8192), 16, 0, 0); } while (0)
; #define PG8_LDA(dst, b, h) do { _Pragma("unroll") for (int m = 0; m < 4; ++m) _Pragma("unroll") for (int k = 0; k < 2; ++k) dst[m][k] = *(const LAS bf16x8*)(lds + PG8_SA(b, h) + aoff + m * 2048 + k * 1024); } while (0)
; #define PG8_MMA(ai, bj, At, Bt) do { __builtin_amdgcn_s_setprio(1); _Pragma("unroll") for (int m = 0; m < 4; ++m) _Pragma("unroll") for (int n = 0; n < 2; ++n) _Pragma("unroll") for (int k = 0; k < 2; ++k) \
;         acc[ai][bj][m][n] = __builtin_amdgcn_mfma_f32_16x16x32_bf16(Bt[n][k], At[m][k], acc[ai][bj][m][n], 0, 0, 0); __builtin_amdgcn_s_setprio(0); } while (0)
; #define PG8_WAIT_V(n) asm volatile("s_waitcnt vmcnt(" #n ")" ::: "memory")
; #define PG8_WAIT_L(n) asm volatile("s_waitcnt lgkmcnt(" #n ")" ::: "memory")
; #define PG8_BAR __builtin_amdgcn_s_barrier()
; #define PG8_SCHED __builtin_amdgcn_sched_barrier(0)
; template <class Epi, class Sched>
; __device__ __forceinline__ void gemm_phase(LAS unsigned char* lds, const int K, const Sched& S, const Epi& E) {
;     ...
;             PG8_LDA(At, 1, 1); PG8_STAGE(PG8_SB(1, 0), b3, voffB); PG8_STAGE(PG8_SB(1, 1), b3 + hstep, voffB); PG8_STAGE(PG8_SA(1, 0), a3, voffA);
;             PG8_WAIT_V(8); PG8_WAIT_L(0); PG8_BAR; PG8_MMA(1, 0, At, B0); PG8_MMA(1, 1, At, B1); PG8_BAR; PG8_SCHED;
;         }
;         if (wr == 0) PG8_BAR;
	s_add_i32 s36, s42, s45
	s_nop 2
	v_lshl_add_u64 v[36:37], v[218:219], 0, s[30:31]
	s_mov_b32 m0, s36
	ds_read_b128 v[186:189], v229 offset:49152
	ds_read_b128 v[190:193], v229 offset:50176
	ds_read_b128 v[194:197], v229 offset:51200
	ds_read_b128 v[198:201], v229 offset:52224
	ds_read_b128 v[202:205], v229 offset:53248
	ds_read_b128 v[206:209], v229 offset:54272
	ds_read_b128 v[210:213], v229 offset:55296
	ds_read_b128 v[214:217], v229 offset:56320
	global_load_lds_dwordx4 v[36:37], off
	s_add_i32 m0, s36, 0x2000
	s_add_u32 s36, s72, 0x80080
	v_lshl_add_u64 v[36:37], v[220:221], 0, s[30:31]
	s_addc_u32 s37, s73, 0
	s_add_i32 s42, s43, s45
	global_load_lds_dwordx4 v[36:37], off
	v_lshl_add_u64 v[36:37], s[36:37], 0, v[172:173]
	s_mov_b32 m0, s42
	s_nop 0
	global_load_lds_dwordx4 v[36:37], off
	v_lshl_add_u64 v[36:37], s[36:37], 0, v[176:177]
	s_add_i32 m0, s42, 0x2000
	s_nop 0
	global_load_lds_dwordx4 v[36:37], off
	v_lshl_add_u64 v[36:37], v[232:233], 0, s[30:31]
	s_mov_b32 m0, s82
	s_nop 0
	global_load_lds_dwordx4 v[36:37], off
	v_lshl_add_u64 v[36:37], v[234:235], 0, s[30:31]
	s_mov_b32 m0, s83
	s_nop 0
	global_load_lds_dwordx4 v[36:37], off
	s_waitcnt vmcnt(8)
	s_waitcnt lgkmcnt(0)
	s_barrier
	s_setprio 1
	v_mfma_f32_16x16x32_bf16 v[36:39], v[24:27], v[186:189], v[84:87]
	v_mfma_f32_16x16x32_bf16 v[84:87], v[28:31], v[190:193], v[36:39]
	v_mfma_f32_16x16x32_bf16 v[36:39], v[32:35], v[186:189], v[80:83]
	v_mfma_f32_16x16x32_bf16 v[80:83], v[72:75], v[190:193], v[36:39]
	v_mfma_f32_16x16x32_bf16 v[36:39], v[24:27], v[194:197], v[68:71]
	v_mfma_f32_16x16x32_bf16 v[68:71], v[28:31], v[198:201], v[36:39]
	v_mfma_f32_16x16x32_bf16 v[36:39], v[32:35], v[194:197], v[64:67]
	v_mfma_f32_16x16x32_bf16 v[64:67], v[72:75], v[198:201], v[36:39]
	v_mfma_f32_16x16x32_bf16 v[36:39], v[24:27], v[202:205], v[52:55]
	v_mfma_f32_16x16x32_bf16 v[52:55], v[28:31], v[206:209], v[36:39]
	v_mfma_f32_16x16x32_bf16 v[36:39], v[32:35], v[202:205], v[48:51]
	v_mfma_f32_16x16x32_bf16 v[0:3], v[24:27], v[210:213], v[0:3]
	v_mfma_f32_16x16x32_bf16 v[48:51], v[72:75], v[206:209], v[36:39]
	v_mfma_f32_16x16x32_bf16 v[36:39], v[28:31], v[214:217], v[0:3]
	v_mfma_f32_16x16x32_bf16 v[0:3], v[32:35], v[210:213], v[4:7]
	v_mfma_f32_16x16x32_bf16 v[32:35], v[72:75], v[214:217], v[0:3]
	v_mfma_f32_16x16x32_bf16 v[0:3], v[152:155], v[186:189], v[8:11]
	v_mfma_f32_16x16x32_bf16 v[76:79], v[156:159], v[190:193], v[0:3]
	v_mfma_f32_16x16x32_bf16 v[0:3], v[160:163], v[186:189], v[12:15]
	v_mfma_f32_16x16x32_bf16 v[72:75], v[164:167], v[190:193], v[0:3]
	v_mfma_f32_16x16x32_bf16 v[0:3], v[152:155], v[194:197], v[60:63]
	v_mfma_f32_16x16x32_bf16 v[60:63], v[156:159], v[198:201], v[0:3]
	v_mfma_f32_16x16x32_bf16 v[0:3], v[160:163], v[194:197], v[56:59]
	v_mfma_f32_16x16x32_bf16 v[56:59], v[164:167], v[198:201], v[0:3]
	v_mfma_f32_16x16x32_bf16 v[0:3], v[152:155], v[202:205], v[44:47]
	v_mfma_f32_16x16x32_bf16 v[44:47], v[156:159], v[206:209], v[0:3]
	v_mfma_f32_16x16x32_bf16 v[0:3], v[160:163], v[202:205], v[40:43]
	v_mfma_f32_16x16x32_bf16 v[40:43], v[164:167], v[206:209], v[0:3]
	v_mfma_f32_16x16x32_bf16 v[0:3], v[152:155], v[210:213], v[16:19]
	v_mfma_f32_16x16x32_bf16 v[28:31], v[156:159], v[214:217], v[0:3]
	v_mfma_f32_16x16x32_bf16 v[0:3], v[160:163], v[210:213], v[20:23]
	v_mfma_f32_16x16x32_bf16 v[24:27], v[164:167], v[214:217], v[0:3]
	s_setprio 0
	s_barrier
	s_add_i32 s9, s9, 2
	s_add_u32 s6, s6, 0x100
	s_addc_u32 s7, s7, 0
	s_add_u32 s1, s1, 0x100
	s_addc_u32 s8, s8, 0
	s_cmp_gt_u32 s9, 29
	s_cbranch_scc0 .LBB0_661
	s_and_b64 vcc, exec, s[34:35]
	s_cbranch_vccz .LBB0_664
	s_barrier

; #define PG8_STAGE(bufoff, gbase, voff) do { _Pragma("unroll") for (int _i = 0; _i < 2; ++_i) \
;         __builtin_amdgcn_global_load_lds((const unsigned*)((const char*)(gbase) + (voff)[_i]), (LAS unsigned*)(lds + (bufoff) + ldsw + _i * 8192), 16, 0, 0); } while (0)
; #define PG8_LDA(dst, b, h) do { _Pragma("unroll") for (int m = 0; m < 4; ++m) _Pragma("unroll") for (int k = 0; k < 2; ++k) dst[m][k] = *(const LAS bf16x8*)(lds + PG8_SA(b, h) + aoff + m * 2048 + k * 1024); } while (0)
; #define PG8_LDB(dst, b, h) do { _Pragma("unroll") for (int n = 0; n < 2; ++n) _Pragma("unroll") for (int k = 0; k < 2; ++k) dst[n][k] = *(const LAS bf16x8*)(lds + PG8_SB(b, h) + boff + n * 2048 + k * 1024); } while (0)
; #define PG8_MMA(ai, bj, At, Bt) do { __builtin_amdgcn_s_setprio(1); _Pragma("unroll") for (int m = 0; m < 4; ++m) _Pragma("unroll") for (int n = 0; n < 2; ++n) _Pragma("unroll") for (int k = 0; k < 2; ++k) \
;         acc[ai][bj][m][n] = __builtin_amdgcn_mfma_f32_16x16x32_bf16(Bt[n][k], At[m][k], acc[ai][bj][m][n], 0, 0, 0); __builtin_amdgcn_s_setprio(0); } while (0)
; #define PG8_WAIT_V(n) asm volatile("s_waitcnt vmcnt(" #n ")" ::: "memory")
; #define PG8_WAIT_L(n) asm volatile("s_waitcnt lgkmcnt(" #n ")" ::: "memory")
; #define PG8_BAR __builtin_amdgcn_s_barrier()
; #define PG8_SCHED __builtin_amdgcn_sched_barrier(0)
; template <class Epi, class Sched>
; __device__ __forceinline__ void gemm_phase(LAS unsigned char* lds, const int K, const Sched& S, const Epi& E) {
;     ...
;         for (int t = 0; t < nt; t += 2) {
;             const bool last = (t == nt - 2);
;             const char* a1 = cA + (size_t)(t + 1) * kstep;
;             const char* a2 = last ? nA : cA + (size_t)(t + 2) * kstep; const char* b2 = last ? nB : cB + (size_t)(t + 2) * kstep;
;             const char* a3 = a2 + kstep; const char* b3 = b2 + kstep;
;             PG8_LDB(B0, 0, 0); PG8_LDB(B1, 0, 1); PG8_SCHED; PG8_LDA(At, 0, 0); PG8_STAGE(PG8_SA(1, 1), a1 + hstep, voffA);
;             PG8_WAIT_V(8); PG8_WAIT_L(0); PG8_BAR; PG8_MMA(0, 0, At, B0); PG8_MMA(0, 1, At, B1); PG8_BAR; PG8_SCHED;
;             PG8_LDA(At, 0, 1); PG8_STAGE(PG8_SB(0, 0), b2, voffB); PG8_STAGE(PG8_SB(0, 1), b2 + hstep, voffB); PG8_STAGE(PG8_SA(0, 0), a2, voffA);
;             PG8_WAIT_V(8); PG8_WAIT_L(0); PG8_BAR; PG8_MMA(1, 0, At, B0); PG8_MMA(1, 1, At, B1); PG8_BAR; PG8_SCHED;
.LBB0_1341:
	ds_read_b128 v[140:143], v147
	ds_read_b128 v[152:155], v147 offset:1024
	ds_read_b128 v[156:159], v147 offset:2048
	ds_read_b128 v[160:163], v147 offset:3072
	ds_read_b128 v[164:167], v148
	ds_read_b128 v[168:171], v148 offset:1024
	ds_read_b128 v[172:175], v148 offset:2048
	ds_read_b128 v[176:179], v148 offset:3072
	s_add_u32 s19, s34, 0xfff80080
	s_addc_u32 s36, s35, -1
	s_cmp_eq_u32 s17, 28
	s_cselect_b32 s39, s23, s36
	s_cselect_b32 s38, s22, s19
	s_cselect_b32 s37, s25, s9
	s_cselect_b32 s36, s24, s8
	v_lshl_add_u64 v[212:213], s[34:35], 0, v[136:137]
	s_add_i32 m0, s27, 0xc000
	ds_read_b128 v[180:183], v149
	ds_read_b128 v[184:187], v149 offset:1024
	ds_read_b128 v[188:191], v149 offset:2048
	ds_read_b128 v[192:195], v149 offset:3072
	ds_read_b128 v[196:199], v149 offset:4096
	ds_read_b128 v[200:203], v149 offset:5120
	ds_read_b128 v[204:207], v149 offset:6144
	ds_read_b128 v[208:211], v149 offset:7168
	global_load_lds_dwordx4 v[212:213], off
	v_lshl_add_u64 v[212:213], s[34:35], 0, v[138:139]
	s_add_i32 m0, s27, 0xe000
	s_nop 0
	global_load_lds_dwordx4 v[212:213], off
	s_waitcnt vmcnt(8)
	s_waitcnt lgkmcnt(0)
	s_barrier
	s_setprio 1
	v_mfma_f32_16x16x32_bf16 v[124:127], v[140:143], v[180:183], v[124:127]
	v_mfma_f32_16x16x32_bf16 v[120:123], v[156:159], v[180:183], v[120:123]
	v_mfma_f32_16x16x32_bf16 v[108:111], v[140:143], v[188:191], v[108:111]
	v_mfma_f32_16x16x32_bf16 v[104:107], v[156:159], v[188:191], v[104:107]
	v_mfma_f32_16x16x32_bf16 v[92:95], v[140:143], v[196:199], v[92:95]
	v_mfma_f32_16x16x32_bf16 v[88:91], v[156:159], v[196:199], v[88:91]
	v_mfma_f32_16x16x32_bf16 v[76:79], v[140:143], v[204:207], v[76:79]
	v_mfma_f32_16x16x32_bf16 v[72:75], v[156:159], v[204:207], v[72:75]
	v_mfma_f32_16x16x32_bf16 v[124:127], v[152:155], v[184:187], v[124:127]
	v_mfma_f32_16x16x32_bf16 v[120:123], v[160:163], v[184:187], v[120:123]
	v_mfma_f32_16x16x32_bf16 v[108:111], v[152:155], v[192:195], v[108:111]
	v_mfma_f32_16x16x32_bf16 v[104:107], v[160:163], v[192:195], v[104:107]
	v_mfma_f32_16x16x32_bf16 v[92:95], v[152:155], v[200:203], v[92:95]
	v_mfma_f32_16x16x32_bf16 v[88:91], v[160:163], v[200:203], v[88:91]
	v_mfma_f32_16x16x32_bf16 v[76:79], v[152:155], v[208:211], v[76:79]
	v_mfma_f32_16x16x32_bf16 v[72:75], v[160:163], v[208:211], v[72:75]
	v_mfma_f32_16x16x32_bf16 v[116:119], v[164:167], v[180:183], v[116:119]
	v_mfma_f32_16x16x32_bf16 v[112:115], v[172:175], v[180:183], v[112:115]
	v_mfma_f32_16x16x32_bf16 v[100:103], v[164:167], v[188:191], v[100:103]
	v_mfma_f32_16x16x32_bf16 v[96:99], v[172:175], v[188:191], v[96:99]
	v_mfma_f32_16x16x32_bf16 v[84:87], v[164:167], v[196:199], v[84:87]
	v_mfma_f32_16x16x32_bf16 v[80:83], v[172:175], v[196:199], v[80:83]
	v_mfma_f32_16x16x32_bf16 v[68:71], v[164:167], v[204:207], v[68:71]
	v_mfma_f32_16x16x32_bf16 v[64:67], v[172:175], v[204:207], v[64:67]
	v_mfma_f32_16x16x32_bf16 v[116:119], v[168:171], v[184:187], v[116:119]
	v_mfma_f32_16x16x32_bf16 v[112:115], v[176:179], v[184:187], v[112:115]
	v_mfma_f32_16x16x32_bf16 v[100:103], v[168:171], v[192:195], v[100:103]
	v_mfma_f32_16x16x32_bf16 v[96:99], v[176:179], v[192:195], v[96:99]
	v_mfma_f32_16x16x32_bf16 v[84:87], v[168:171], v[200:203], v[84:87]
	v_mfma_f32_16x16x32_bf16 v[80:83], v[176:179], v[200:203], v[80:83]
	v_mfma_f32_16x16x32_bf16 v[68:71], v[168:171], v[208:211], v[68:71]
	v_mfma_f32_16x16x32_bf16 v[64:67], v[176:179], v[208:211], v[64:67]
	s_setprio 0
	s_barrier
	s_add_i32 s19, s48, s40
	v_lshl_add_u64 v[212:213], s[36:37], 0, v[130:131]
	s_mov_b32 m0, s19
	ds_read_b128 v[180:183], v149 offset:16384
	ds_read_b128 v[184:187], v149 offset:17408
	ds_read_b128 v[188:191], v149 offset:18432
	ds_read_b128 v[192:195], v149 offset:19456
	ds_read_b128 v[196:199], v149 offset:20480
	ds_read_b128 v[200:203], v149 offset:21504
	ds_read_b128 v[204:207], v149 offset:22528
	ds_read_b128 v[208:211], v149 offset:23552
	global_load_lds_dwordx4 v[212:213], off
	s_add_i32 m0, s19, 0x2000
	s_add_u32 s50, s36, 0x80000
	v_lshl_add_u64 v[214:215], s[36:37], 0, v[134:135]
	s_addc_u32 s51, s37, 0
	s_add_i32 s19, s49, s40
	global_load_lds_dwordx4 v[214:215], off
	v_lshl_add_u64 v[216:217], s[50:51], 0, v[130:131]
	s_mov_b32 m0, s19
	v_lshl_add_u64 v[218:219], s[38:39], 0, v[132:133]
	global_load_lds_dwordx4 v[216:217], off
	v_lshl_add_u64 v[216:217], s[50:51], 0, v[134:135]
	s_add_i32 m0, s19, 0x2000
	s_nop 0
	global_load_lds_dwordx4 v[216:217], off
	v_lshl_add_u64 v[216:217], s[38:39], 0, v[128:129]
	s_mov_b32 m0, s27
	s_nop 0
	global_load_lds_dwordx4 v[216:217], off
	s_mov_b32 m0, s31
	s_nop 0
	global_load_lds_dwordx4 v[218:219], off
	s_waitcnt vmcnt(8)
	s_waitcnt lgkmcnt(0)
	s_barrier
; #define PG8_STAGE(bufoff, gbase, voff) do { _Pragma("unroll") for (int _i = 0; _i < 2; ++_i) \
;         __builtin_amdgcn_global_load_lds((const unsigned*)((const char*)(gbase) + (voff)[_i]), (LAS unsigned*)(lds + (bufoff) + ldsw + _i * 8192), 16, 0, 0); } while (0)
; #define PG8_LDA(dst, b, h) do { _Pragma("unroll") for (int m = 0; m < 4; ++m) _Pragma("unroll") for (int k = 0; k < 2; ++k) dst[m][k] = *(const LAS bf16x8*)(lds + PG8_SA(b, h) + aoff + m * 2048 + k * 1024); } while (0)
; #define PG8_LDB(dst, b, h) do { _Pragma("unroll") for (int n = 0; n < 2; ++n) _Pragma("unroll") for (int k = 0; k < 2; ++k) dst[n][k] = *(const LAS bf16x8*)(lds + PG8_SB(b, h) + boff + n * 2048 + k * 1024); } while (0)
; #define PG8_MMA(ai, bj, At, Bt) do { __builtin_amdgcn_s_setprio(1); _Pragma("unroll") for (int m = 0; m < 4; ++m) _Pragma("unroll") for (int n = 0; n < 2; ++n) _Pragma("unroll") for (int k = 0; k < 2; ++k) \
;         acc[ai][bj][m][n] = __builtin_amdgcn_mfma_f32_16x16x32_bf16(Bt[n][k], At[m][k], acc[ai][bj][m][n], 0, 0, 0); __builtin_amdgcn_s_setprio(0); } while (0)
; #define PG8_WAIT_V(n) asm volatile("s_waitcnt vmcnt(" #n ")" ::: "memory")
; #define PG8_WAIT_L(n) asm volatile("s_waitcnt lgkmcnt(" #n ")" ::: "memory")
; #define PG8_BAR __builtin_amdgcn_s_barrier()
; #define PG8_SCHED __builtin_amdgcn_sched_barrier(0)
; template <class Epi, class Sched>
; __device__ __forceinline__ void gemm_phase(LAS unsigned char* lds, const int K, const Sched& S, const Epi& E) {
;     ...
;             PG8_WAIT_V(8); PG8_WAIT_L(0); PG8_BAR; PG8_MMA(1, 0, At, B0); PG8_MMA(1, 1, At, B1); PG8_BAR; PG8_SCHED;
;             PG8_LDB(B0, 1, 0); PG8_LDB(B1, 1, 1); PG8_SCHED; PG8_LDA(At, 1, 0); PG8_STAGE(PG8_SA(0, 1), a2 + hstep, voffA);
;             PG8_WAIT_V(8); PG8_WAIT_L(0); PG8_BAR; PG8_MMA(0, 0, At, B0); PG8_MMA(0, 1, At, B1); PG8_BAR; PG8_SCHED;
	s_setprio 1
	v_mfma_f32_16x16x32_bf16 v[60:63], v[140:143], v[180:183], v[60:63]
	v_mfma_f32_16x16x32_bf16 v[56:59], v[156:159], v[180:183], v[56:59]
	v_mfma_f32_16x16x32_bf16 v[44:47], v[140:143], v[188:191], v[44:47]
	v_mfma_f32_16x16x32_bf16 v[40:43], v[156:159], v[188:191], v[40:43]
	v_mfma_f32_16x16x32_bf16 v[28:31], v[140:143], v[196:199], v[28:31]
	v_mfma_f32_16x16x32_bf16 v[24:27], v[156:159], v[196:199], v[24:27]
	v_mfma_f32_16x16x32_bf16 v[12:15], v[140:143], v[204:207], v[12:15]
	v_mfma_f32_16x16x32_bf16 v[8:11], v[156:159], v[204:207], v[8:11]
	v_mfma_f32_16x16x32_bf16 v[60:63], v[152:155], v[184:187], v[60:63]
	v_mfma_f32_16x16x32_bf16 v[56:59], v[160:163], v[184:187], v[56:59]
	v_mfma_f32_16x16x32_bf16 v[44:47], v[152:155], v[192:195], v[44:47]
	v_mfma_f32_16x16x32_bf16 v[40:43], v[160:163], v[192:195], v[40:43]
	v_mfma_f32_16x16x32_bf16 v[28:31], v[152:155], v[200:203], v[28:31]
	v_mfma_f32_16x16x32_bf16 v[24:27], v[160:163], v[200:203], v[24:27]
	v_mfma_f32_16x16x32_bf16 v[12:15], v[152:155], v[208:211], v[12:15]
	v_mfma_f32_16x16x32_bf16 v[8:11], v[160:163], v[208:211], v[8:11]
	v_mfma_f32_16x16x32_bf16 v[52:55], v[164:167], v[180:183], v[52:55]
	v_mfma_f32_16x16x32_bf16 v[48:51], v[172:175], v[180:183], v[48:51]
	v_mfma_f32_16x16x32_bf16 v[36:39], v[164:167], v[188:191], v[36:39]
	v_mfma_f32_16x16x32_bf16 v[32:35], v[172:175], v[188:191], v[32:35]
	v_mfma_f32_16x16x32_bf16 v[20:23], v[164:167], v[196:199], v[20:23]
	v_mfma_f32_16x16x32_bf16 v[16:19], v[172:175], v[196:199], v[16:19]
	v_mfma_f32_16x16x32_bf16 v[4:7], v[164:167], v[204:207], v[4:7]
	v_mfma_f32_16x16x32_bf16 v[0:3], v[172:175], v[204:207], v[0:3]
	v_mfma_f32_16x16x32_bf16 v[52:55], v[168:171], v[184:187], v[52:55]
	v_mfma_f32_16x16x32_bf16 v[48:51], v[176:179], v[184:187], v[48:51]
	v_mfma_f32_16x16x32_bf16 v[36:39], v[168:171], v[192:195], v[36:39]
	v_mfma_f32_16x16x32_bf16 v[32:35], v[176:179], v[192:195], v[32:35]
	v_mfma_f32_16x16x32_bf16 v[20:23], v[168:171], v[200:203], v[20:23]
	v_mfma_f32_16x16x32_bf16 v[16:19], v[176:179], v[200:203], v[16:19]
	v_mfma_f32_16x16x32_bf16 v[4:7], v[168:171], v[208:211], v[4:7]
	v_mfma_f32_16x16x32_bf16 v[0:3], v[176:179], v[208:211], v[0:3]
	s_setprio 0
	s_barrier
	s_add_i32 s19, 0, 0x18000
	v_add_u32_e32 v151, s19, v146
	s_add_i32 s50, 0, 0x1c000
	ds_read_b128 v[140:143], v151
	ds_read_b128 v[152:155], v151 offset:1024
	ds_read_b128 v[156:159], v151 offset:2048
	ds_read_b128 v[160:163], v151 offset:3072
	v_add_u32_e32 v151, s50, v146
	ds_read_b128 v[164:167], v151
	ds_read_b128 v[168:171], v151 offset:1024
	ds_read_b128 v[172:175], v151 offset:2048
	ds_read_b128 v[176:179], v151 offset:3072
	s_add_u32 s38, s38, 0x80000
	s_addc_u32 s39, s39, 0
	s_mov_b32 m0, s41
	v_lshl_add_u64 v[220:221], s[38:39], 0, v[128:129]
	ds_read_b128 v[180:183], v149 offset:32768
	ds_read_b128 v[184:187], v149 offset:33792
	ds_read_b128 v[188:191], v149 offset:34816
	ds_read_b128 v[192:195], v149 offset:35840
	ds_read_b128 v[196:199], v149 offset:36864
	ds_read_b128 v[200:203], v149 offset:37888
	ds_read_b128 v[204:207], v149 offset:38912
	ds_read_b128 v[208:211], v149 offset:39936
	global_load_lds_dwordx4 v[220:221], off
	v_lshl_add_u64 v[220:221], s[38:39], 0, v[132:133]
	s_mov_b32 m0, s42
	s_nop 0
	global_load_lds_dwordx4 v[220:221], off
	s_waitcnt vmcnt(8)
	s_waitcnt lgkmcnt(0)
	s_barrier
	s_setprio 1
	v_mfma_f32_16x16x32_bf16 v[124:127], v[140:143], v[180:183], v[124:127]
	v_mfma_f32_16x16x32_bf16 v[120:123], v[156:159], v[180:183], v[120:123]
	v_mfma_f32_16x16x32_bf16 v[108:111], v[140:143], v[188:191], v[108:111]
	v_mfma_f32_16x16x32_bf16 v[104:107], v[156:159], v[188:191], v[104:107]
	v_mfma_f32_16x16x32_bf16 v[92:95], v[140:143], v[196:199], v[92:95]
	v_mfma_f32_16x16x32_bf16 v[88:91], v[156:159], v[196:199], v[88:91]
	v_mfma_f32_16x16x32_bf16 v[76:79], v[140:143], v[204:207], v[76:79]
	v_mfma_f32_16x16x32_bf16 v[72:75], v[156:159], v[204:207], v[72:75]
	v_mfma_f32_16x16x32_bf16 v[124:127], v[152:155], v[184:187], v[124:127]
	v_mfma_f32_16x16x32_bf16 v[120:123], v[160:163], v[184:187], v[120:123]
	v_mfma_f32_16x16x32_bf16 v[108:111], v[152:155], v[192:195], v[108:111]
	v_mfma_f32_16x16x32_bf16 v[104:107], v[160:163], v[192:195], v[104:107]
	v_mfma_f32_16x16x32_bf16 v[92:95], v[152:155], v[200:203], v[92:95]
	v_mfma_f32_16x16x32_bf16 v[88:91], v[160:163], v[200:203], v[88:91]
	v_mfma_f32_16x16x32_bf16 v[76:79], v[152:155], v[208:211], v[76:79]
	v_mfma_f32_16x16x32_bf16 v[72:75], v[160:163], v[208:211], v[72:75]
	v_mfma_f32_16x16x32_bf16 v[116:119], v[164:167], v[180:183], v[116:119]
	v_mfma_f32_16x16x32_bf16 v[112:115], v[172:175], v[180:183], v[112:115]
	v_mfma_f32_16x16x32_bf16 v[100:103], v[164:167], v[188:191], v[100:103]
	v_mfma_f32_16x16x32_bf16 v[96:99], v[172:175], v[188:191], v[96:99]
	v_mfma_f32_16x16x32_bf16 v[84:87], v[164:167], v[196:199], v[84:87]
	v_mfma_f32_16x16x32_bf16 v[80:83], v[172:175], v[196:199], v[80:83]
	v_mfma_f32_16x16x32_bf16 v[68:71], v[164:167], v[204:207], v[68:71]
	v_mfma_f32_16x16x32_bf16 v[64:67], v[172:175], v[204:207], v[64:67]
	v_mfma_f32_16x16x32_bf16 v[116:119], v[168:171], v[184:187], v[116:119]
	v_mfma_f32_16x16x32_bf16 v[112:115], v[176:179], v[184:187], v[112:115]
	v_mfma_f32_16x16x32_bf16 v[100:103], v[168:171], v[192:195], v[100:103]
	v_mfma_f32_16x16x32_bf16 v[96:99], v[176:179], v[192:195], v[96:99]
	v_mfma_f32_16x16x32_bf16 v[84:87], v[168:171], v[200:203], v[84:87]
	v_mfma_f32_16x16x32_bf16 v[80:83], v[176:179], v[200:203], v[80:83]
	v_mfma_f32_16x16x32_bf16 v[68:71], v[168:171], v[208:211], v[68:71]
	v_mfma_f32_16x16x32_bf16 v[64:67], v[176:179], v[208:211], v[64:67]
	s_setprio 0
	s_barrier
; #define PG8_STAGE(bufoff, gbase, voff) do { _Pragma("unroll") for (int _i = 0; _i < 2; ++_i) \
;         __builtin_amdgcn_global_load_lds((const unsigned*)((const char*)(gbase) + (voff)[_i]), (LAS unsigned*)(lds + (bufoff) + ldsw + _i * 8192), 16, 0, 0); } while (0)
; #define PG8_LDA(dst, b, h) do { _Pragma("unroll") for (int m = 0; m < 4; ++m) _Pragma("unroll") for (int k = 0; k < 2; ++k) dst[m][k] = *(const LAS bf16x8*)(lds + PG8_SA(b, h) + aoff + m * 2048 + k * 1024); } while (0)
; #define PG8_MMA(ai, bj, At, Bt) do { __builtin_amdgcn_s_setprio(1); _Pragma("unroll") for (int m = 0; m < 4; ++m) _Pragma("unroll") for (int n = 0; n < 2; ++n) _Pragma("unroll") for (int k = 0; k < 2; ++k) \
;         acc[ai][bj][m][n] = __builtin_amdgcn_mfma_f32_16x16x32_bf16(Bt[n][k], At[m][k], acc[ai][bj][m][n], 0, 0, 0); __builtin_amdgcn_s_setprio(0); } while (0)
; #define PG8_WAIT_V(n) asm volatile("s_waitcnt vmcnt(" #n ")" ::: "memory")
; #define PG8_WAIT_L(n) asm volatile("s_waitcnt lgkmcnt(" #n ")" ::: "memory")
; #define PG8_BAR __builtin_amdgcn_s_barrier()
; #define PG8_SCHED __builtin_amdgcn_sched_barrier(0)
; template <class Epi, class Sched>
; __device__ __forceinline__ void gemm_phase(LAS unsigned char* lds, const int K, const Sched& S, const Epi& E) {
;     ...
;             PG8_LDA(At, 1, 1); PG8_STAGE(PG8_SB(1, 0), b3, voffB); PG8_STAGE(PG8_SB(1, 1), b3 + hstep, voffB); PG8_STAGE(PG8_SA(1, 0), a3, voffA);
;             PG8_WAIT_V(8); PG8_WAIT_L(0); PG8_BAR; PG8_MMA(1, 0, At, B0); PG8_MMA(1, 1, At, B1); PG8_BAR; PG8_SCHED;
;         }
;         if (wr == 0) PG8_BAR;
	s_add_i32 s19, s19, s40
	v_lshl_add_u64 v[212:213], v[212:213], 0, s[12:13]
	s_mov_b32 m0, s19
	ds_read_b128 v[180:183], v149 offset:49152
	ds_read_b128 v[184:187], v149 offset:50176
	ds_read_b128 v[188:191], v149 offset:51200
	ds_read_b128 v[192:195], v149 offset:52224
	ds_read_b128 v[196:199], v149 offset:53248
	ds_read_b128 v[200:203], v149 offset:54272
	ds_read_b128 v[204:207], v149 offset:55296
	ds_read_b128 v[208:211], v149 offset:56320
	global_load_lds_dwordx4 v[212:213], off
	s_add_i32 m0, s19, 0x2000
	s_add_u32 s36, s36, 0x80080
	v_lshl_add_u64 v[212:213], v[214:215], 0, s[12:13]
	s_addc_u32 s37, s37, 0
	s_add_i32 s19, s50, s40
	global_load_lds_dwordx4 v[212:213], off
	v_lshl_add_u64 v[212:213], s[36:37], 0, v[130:131]
	s_mov_b32 m0, s19
	s_nop 0
	global_load_lds_dwordx4 v[212:213], off
	v_lshl_add_u64 v[212:213], s[36:37], 0, v[134:135]
	s_add_i32 m0, s19, 0x2000
	s_nop 0
	global_load_lds_dwordx4 v[212:213], off
	v_lshl_add_u64 v[212:213], v[216:217], 0, s[12:13]
	s_mov_b32 m0, s46
	s_nop 0
	global_load_lds_dwordx4 v[212:213], off
	v_lshl_add_u64 v[212:213], v[218:219], 0, s[12:13]
	s_mov_b32 m0, s47
	s_nop 0
	global_load_lds_dwordx4 v[212:213], off
	s_waitcnt vmcnt(8)
	s_waitcnt lgkmcnt(0)
	s_barrier
	s_setprio 1
	v_mfma_f32_16x16x32_bf16 v[60:63], v[140:143], v[180:183], v[60:63]
	v_mfma_f32_16x16x32_bf16 v[56:59], v[156:159], v[180:183], v[56:59]
	v_mfma_f32_16x16x32_bf16 v[44:47], v[140:143], v[188:191], v[44:47]
	v_mfma_f32_16x16x32_bf16 v[40:43], v[156:159], v[188:191], v[40:43]
	v_mfma_f32_16x16x32_bf16 v[28:31], v[140:143], v[196:199], v[28:31]
	v_mfma_f32_16x16x32_bf16 v[24:27], v[156:159], v[196:199], v[24:27]
	v_mfma_f32_16x16x32_bf16 v[12:15], v[140:143], v[204:207], v[12:15]
	v_mfma_f32_16x16x32_bf16 v[8:11], v[156:159], v[204:207], v[8:11]
	v_mfma_f32_16x16x32_bf16 v[60:63], v[152:155], v[184:187], v[60:63]
	v_mfma_f32_16x16x32_bf16 v[56:59], v[160:163], v[184:187], v[56:59]
	v_mfma_f32_16x16x32_bf16 v[44:47], v[152:155], v[192:195], v[44:47]
	v_mfma_f32_16x16x32_bf16 v[40:43], v[160:163], v[192:195], v[40:43]
	v_mfma_f32_16x16x32_bf16 v[28:31], v[152:155], v[200:203], v[28:31]
	v_mfma_f32_16x16x32_bf16 v[24:27], v[160:163], v[200:203], v[24:27]
	v_mfma_f32_16x16x32_bf16 v[12:15], v[152:155], v[208:211], v[12:15]
	v_mfma_f32_16x16x32_bf16 v[8:11], v[160:163], v[208:211], v[8:11]
	v_mfma_f32_16x16x32_bf16 v[52:55], v[164:167], v[180:183], v[52:55]
	v_mfma_f32_16x16x32_bf16 v[48:51], v[172:175], v[180:183], v[48:51]
	v_mfma_f32_16x16x32_bf16 v[36:39], v[164:167], v[188:191], v[36:39]
	v_mfma_f32_16x16x32_bf16 v[32:35], v[172:175], v[188:191], v[32:35]
	v_mfma_f32_16x16x32_bf16 v[20:23], v[164:167], v[196:199], v[20:23]
	v_mfma_f32_16x16x32_bf16 v[16:19], v[172:175], v[196:199], v[16:19]
	v_mfma_f32_16x16x32_bf16 v[4:7], v[164:167], v[204:207], v[4:7]
	v_mfma_f32_16x16x32_bf16 v[0:3], v[172:175], v[204:207], v[0:3]
	v_mfma_f32_16x16x32_bf16 v[52:55], v[168:171], v[184:187], v[52:55]
	v_mfma_f32_16x16x32_bf16 v[48:51], v[176:179], v[184:187], v[48:51]
	v_mfma_f32_16x16x32_bf16 v[36:39], v[168:171], v[192:195], v[36:39]
	v_mfma_f32_16x16x32_bf16 v[32:35], v[176:179], v[192:195], v[32:35]
	v_mfma_f32_16x16x32_bf16 v[20:23], v[168:171], v[200:203], v[20:23]
	v_mfma_f32_16x16x32_bf16 v[16:19], v[176:179], v[200:203], v[16:19]
	v_mfma_f32_16x16x32_bf16 v[4:7], v[168:171], v[208:211], v[4:7]
	v_mfma_f32_16x16x32_bf16 v[0:3], v[176:179], v[208:211], v[0:3]
	s_setprio 0
	s_barrier
	s_add_i32 s17, s17, 2
	s_add_u32 s34, s34, 0x100
	s_addc_u32 s35, s35, 0
	s_add_u32 s8, s8, 0x100
	s_addc_u32 s9, s9, 0
	s_cmp_gt_u32 s17, 29
	s_cbranch_scc0 .LBB0_1341
	s_and_b64 vcc, exec, s[14:15]
	s_cbranch_vccz .LBB0_1344
	s_barrier

; #define PG8_STAGE(bufoff, gbase, voff) do { _Pragma("unroll") for (int _i = 0; _i < 2; ++_i) \
;         __builtin_amdgcn_global_load_lds((const unsigned*)((const char*)(gbase) + (voff)[_i]), (LAS unsigned*)(lds + (bufoff) + ldsw + _i * 8192), 16, 0, 0); } while (0)
; #define PG8_LDA(dst, b, h) do { _Pragma("unroll") for (int m = 0; m < 4; ++m) _Pragma("unroll") for (int k = 0; k < 2; ++k) dst[m][k] = *(const LAS bf16x8*)(lds + PG8_SA(b, h) + aoff + m * 2048 + k * 1024); } while (0)
; #define PG8_LDB(dst, b, h) do { _Pragma("unroll") for (int n = 0; n < 2; ++n) _Pragma("unroll") for (int k = 0; k < 2; ++k) dst[n][k] = *(const LAS bf16x8*)(lds + PG8_SB(b, h) + boff + n * 2048 + k * 1024); } while (0)
; #define PG8_MMA(ai, bj, At, Bt) do { __builtin_amdgcn_s_setprio(1); _Pragma("unroll") for (int m = 0; m < 4; ++m) _Pragma("unroll") for (int n = 0; n < 2; ++n) _Pragma("unroll") for (int k = 0; k < 2; ++k) \
;         acc[ai][bj][m][n] = __builtin_amdgcn_mfma_f32_16x16x32_bf16(Bt[n][k], At[m][k], acc[ai][bj][m][n], 0, 0, 0); __builtin_amdgcn_s_setprio(0); } while (0)
; #define PG8_WAIT_V(n) asm volatile("s_waitcnt vmcnt(" #n ")" ::: "memory")
; #define PG8_WAIT_L(n) asm volatile("s_waitcnt lgkmcnt(" #n ")" ::: "memory")
; #define PG8_BAR __builtin_amdgcn_s_barrier()
; #define PG8_SCHED __builtin_amdgcn_sched_barrier(0)
; template <class Epi, class Sched>
; __device__ __forceinline__ void gemm_phase(LAS unsigned char* lds, const int K, const Sched& S, const Epi& E) {
;     ...
;         for (int t = 0; t < nt; t += 2) {
;             const bool last = (t == nt - 2);
;             const char* a1 = cA + (size_t)(t + 1) * kstep;
;             const char* a2 = last ? nA : cA + (size_t)(t + 2) * kstep; const char* b2 = last ? nB : cB + (size_t)(t + 2) * kstep;
;             const char* a3 = a2 + kstep; const char* b3 = b2 + kstep;
;             PG8_LDB(B0, 0, 0); PG8_LDB(B1, 0, 1); PG8_SCHED; PG8_LDA(At, 0, 0); PG8_STAGE(PG8_SA(1, 1), a1 + hstep, voffA);
;             PG8_WAIT_V(8); PG8_WAIT_L(0); PG8_BAR; PG8_MMA(0, 0, At, B0); PG8_MMA(0, 1, At, B1); PG8_BAR; PG8_SCHED;
;             PG8_LDA(At, 0, 1); PG8_STAGE(PG8_SB(0, 0), b2, voffB); PG8_STAGE(PG8_SB(0, 1), b2 + hstep, voffB); PG8_STAGE(PG8_SA(0, 0), a2, voffA);
;             PG8_WAIT_V(8); PG8_WAIT_L(0); PG8_BAR; PG8_MMA(1, 0, At, B0); PG8_MMA(1, 1, At, B1); PG8_BAR; PG8_SCHED;
.LBB0_1433:
	ds_read_b128 v[140:143], v151
	ds_read_b128 v[144:147], v151 offset:1024
	ds_read_b128 v[156:159], v151 offset:2048
	ds_read_b128 v[160:163], v151 offset:3072
	ds_read_b128 v[164:167], v152
	ds_read_b128 v[168:171], v152 offset:1024
	ds_read_b128 v[172:175], v152 offset:2048
	ds_read_b128 v[176:179], v152 offset:3072
	s_add_u32 s25, s34, 0xfff80080
	s_addc_u32 s36, s35, -1
	s_cmp_eq_u32 s23, 28
	s_cselect_b32 s39, s27, s36
	s_cselect_b32 s38, s26, s25
	s_cselect_b32 s37, s31, s9
	s_cselect_b32 s36, s30, s8
	v_lshl_add_u64 v[212:213], s[34:35], 0, v[136:137]
	s_add_i32 m0, s42, 0xc000
	ds_read_b128 v[180:183], v153
	ds_read_b128 v[184:187], v153 offset:1024
	ds_read_b128 v[188:191], v153 offset:2048
	ds_read_b128 v[192:195], v153 offset:3072
	ds_read_b128 v[196:199], v153 offset:4096
	ds_read_b128 v[200:203], v153 offset:5120
	ds_read_b128 v[204:207], v153 offset:6144
	ds_read_b128 v[208:211], v153 offset:7168
	global_load_lds_dwordx4 v[212:213], off
	v_lshl_add_u64 v[212:213], s[34:35], 0, v[138:139]
	s_add_i32 m0, s42, 0xe000
	s_nop 0
	global_load_lds_dwordx4 v[212:213], off
	s_waitcnt vmcnt(8)
	s_waitcnt lgkmcnt(0)
	s_barrier
	s_setprio 1
	v_mfma_f32_16x16x32_bf16 v[124:127], v[140:143], v[180:183], v[124:127]
	v_mfma_f32_16x16x32_bf16 v[120:123], v[156:159], v[180:183], v[120:123]
	v_mfma_f32_16x16x32_bf16 v[108:111], v[140:143], v[188:191], v[108:111]
	v_mfma_f32_16x16x32_bf16 v[104:107], v[156:159], v[188:191], v[104:107]
	v_mfma_f32_16x16x32_bf16 v[92:95], v[140:143], v[196:199], v[92:95]
	v_mfma_f32_16x16x32_bf16 v[88:91], v[156:159], v[196:199], v[88:91]
	v_mfma_f32_16x16x32_bf16 v[76:79], v[140:143], v[204:207], v[76:79]
	v_mfma_f32_16x16x32_bf16 v[72:75], v[156:159], v[204:207], v[72:75]
	v_mfma_f32_16x16x32_bf16 v[124:127], v[144:147], v[184:187], v[124:127]
	v_mfma_f32_16x16x32_bf16 v[120:123], v[160:163], v[184:187], v[120:123]
	v_mfma_f32_16x16x32_bf16 v[108:111], v[144:147], v[192:195], v[108:111]
	v_mfma_f32_16x16x32_bf16 v[104:107], v[160:163], v[192:195], v[104:107]
	v_mfma_f32_16x16x32_bf16 v[92:95], v[144:147], v[200:203], v[92:95]
	v_mfma_f32_16x16x32_bf16 v[88:91], v[160:163], v[200:203], v[88:91]
	v_mfma_f32_16x16x32_bf16 v[76:79], v[144:147], v[208:211], v[76:79]
	v_mfma_f32_16x16x32_bf16 v[72:75], v[160:163], v[208:211], v[72:75]
	v_mfma_f32_16x16x32_bf16 v[116:119], v[164:167], v[180:183], v[116:119]
	v_mfma_f32_16x16x32_bf16 v[112:115], v[172:175], v[180:183], v[112:115]
	v_mfma_f32_16x16x32_bf16 v[100:103], v[164:167], v[188:191], v[100:103]
	v_mfma_f32_16x16x32_bf16 v[96:99], v[172:175], v[188:191], v[96:99]
	v_mfma_f32_16x16x32_bf16 v[84:87], v[164:167], v[196:199], v[84:87]
	v_mfma_f32_16x16x32_bf16 v[80:83], v[172:175], v[196:199], v[80:83]
	v_mfma_f32_16x16x32_bf16 v[68:71], v[164:167], v[204:207], v[68:71]
	v_mfma_f32_16x16x32_bf16 v[64:67], v[172:175], v[204:207], v[64:67]
	v_mfma_f32_16x16x32_bf16 v[116:119], v[168:171], v[184:187], v[116:119]
	v_mfma_f32_16x16x32_bf16 v[112:115], v[176:179], v[184:187], v[112:115]
	v_mfma_f32_16x16x32_bf16 v[100:103], v[168:171], v[192:195], v[100:103]
	v_mfma_f32_16x16x32_bf16 v[96:99], v[176:179], v[192:195], v[96:99]
	v_mfma_f32_16x16x32_bf16 v[84:87], v[168:171], v[200:203], v[84:87]
	v_mfma_f32_16x16x32_bf16 v[80:83], v[176:179], v[200:203], v[80:83]
	v_mfma_f32_16x16x32_bf16 v[68:71], v[168:171], v[208:211], v[68:71]
	v_mfma_f32_16x16x32_bf16 v[64:67], v[176:179], v[208:211], v[64:67]
	s_setprio 0
	s_barrier
	s_add_i32 s25, s49, s40
	v_lshl_add_u64 v[212:213], s[36:37], 0, v[132:133]
	s_mov_b32 m0, s25
	ds_read_b128 v[180:183], v153 offset:16384
	ds_read_b128 v[184:187], v153 offset:17408
	ds_read_b128 v[188:191], v153 offset:18432
	ds_read_b128 v[192:195], v153 offset:19456
	ds_read_b128 v[196:199], v153 offset:20480
	ds_read_b128 v[200:203], v153 offset:21504
	ds_read_b128 v[204:207], v153 offset:22528
	ds_read_b128 v[208:211], v153 offset:23552
	global_load_lds_dwordx4 v[212:213], off
	s_add_i32 m0, s25, 0x2000
	s_add_u32 s62, s36, 0x80000
	v_lshl_add_u64 v[214:215], s[36:37], 0, v[128:129]
	s_addc_u32 s63, s37, 0
	s_add_i32 s25, s50, s40
	global_load_lds_dwordx4 v[214:215], off
	v_lshl_add_u64 v[216:217], s[62:63], 0, v[132:133]
	s_mov_b32 m0, s25
	v_lshl_add_u64 v[218:219], s[38:39], 0, v[130:131]
	global_load_lds_dwordx4 v[216:217], off
	v_lshl_add_u64 v[216:217], s[62:63], 0, v[128:129]
	s_add_i32 m0, s25, 0x2000
	s_nop 0
	global_load_lds_dwordx4 v[216:217], off
	v_lshl_add_u64 v[216:217], s[38:39], 0, v[134:135]
	s_mov_b32 m0, s42
	s_nop 0
	global_load_lds_dwordx4 v[216:217], off
	s_mov_b32 m0, s43
	s_nop 0
	global_load_lds_dwordx4 v[218:219], off
	s_waitcnt vmcnt(8)
	s_waitcnt lgkmcnt(0)
	s_barrier
; #define PG8_STAGE(bufoff, gbase, voff) do { _Pragma("unroll") for (int _i = 0; _i < 2; ++_i) \
;         __builtin_amdgcn_global_load_lds((const unsigned*)((const char*)(gbase) + (voff)[_i]), (LAS unsigned*)(lds + (bufoff) + ldsw + _i * 8192), 16, 0, 0); } while (0)
; #define PG8_LDA(dst, b, h) do { _Pragma("unroll") for (int m = 0; m < 4; ++m) _Pragma("unroll") for (int k = 0; k < 2; ++k) dst[m][k] = *(const LAS bf16x8*)(lds + PG8_SA(b, h) + aoff + m * 2048 + k * 1024); } while (0)
; #define PG8_LDB(dst, b, h) do { _Pragma("unroll") for (int n = 0; n < 2; ++n) _Pragma("unroll") for (int k = 0; k < 2; ++k) dst[n][k] = *(const LAS bf16x8*)(lds + PG8_SB(b, h) + boff + n * 2048 + k * 1024); } while (0)
; #define PG8_MMA(ai, bj, At, Bt) do { __builtin_amdgcn_s_setprio(1); _Pragma("unroll") for (int m = 0; m < 4; ++m) _Pragma("unroll") for (int n = 0; n < 2; ++n) _Pragma("unroll") for (int k = 0; k < 2; ++k) \
;         acc[ai][bj][m][n] = __builtin_amdgcn_mfma_f32_16x16x32_bf16(Bt[n][k], At[m][k], acc[ai][bj][m][n], 0, 0, 0); __builtin_amdgcn_s_setprio(0); } while (0)
; #define PG8_WAIT_V(n) asm volatile("s_waitcnt vmcnt(" #n ")" ::: "memory")
; #define PG8_WAIT_L(n) asm volatile("s_waitcnt lgkmcnt(" #n ")" ::: "memory")
; #define PG8_BAR __builtin_amdgcn_s_barrier()
; #define PG8_SCHED __builtin_amdgcn_sched_barrier(0)
; template <class Epi, class Sched>
; __device__ __forceinline__ void gemm_phase(LAS unsigned char* lds, const int K, const Sched& S, const Epi& E) {
;     ...
;             PG8_WAIT_V(8); PG8_WAIT_L(0); PG8_BAR; PG8_MMA(1, 0, At, B0); PG8_MMA(1, 1, At, B1); PG8_BAR; PG8_SCHED;
;             PG8_LDB(B0, 1, 0); PG8_LDB(B1, 1, 1); PG8_SCHED; PG8_LDA(At, 1, 0); PG8_STAGE(PG8_SA(0, 1), a2 + hstep, voffA);
;             PG8_WAIT_V(8); PG8_WAIT_L(0); PG8_BAR; PG8_MMA(0, 0, At, B0); PG8_MMA(0, 1, At, B1); PG8_BAR; PG8_SCHED;
	s_setprio 1
	v_mfma_f32_16x16x32_bf16 v[60:63], v[140:143], v[180:183], v[60:63]
	v_mfma_f32_16x16x32_bf16 v[56:59], v[156:159], v[180:183], v[56:59]
	v_mfma_f32_16x16x32_bf16 v[44:47], v[140:143], v[188:191], v[44:47]
	v_mfma_f32_16x16x32_bf16 v[40:43], v[156:159], v[188:191], v[40:43]
	v_mfma_f32_16x16x32_bf16 v[28:31], v[140:143], v[196:199], v[28:31]
	v_mfma_f32_16x16x32_bf16 v[24:27], v[156:159], v[196:199], v[24:27]
	v_mfma_f32_16x16x32_bf16 v[12:15], v[140:143], v[204:207], v[12:15]
	v_mfma_f32_16x16x32_bf16 v[8:11], v[156:159], v[204:207], v[8:11]
	v_mfma_f32_16x16x32_bf16 v[60:63], v[144:147], v[184:187], v[60:63]
	v_mfma_f32_16x16x32_bf16 v[56:59], v[160:163], v[184:187], v[56:59]
	v_mfma_f32_16x16x32_bf16 v[44:47], v[144:147], v[192:195], v[44:47]
	v_mfma_f32_16x16x32_bf16 v[40:43], v[160:163], v[192:195], v[40:43]
	v_mfma_f32_16x16x32_bf16 v[28:31], v[144:147], v[200:203], v[28:31]
	v_mfma_f32_16x16x32_bf16 v[24:27], v[160:163], v[200:203], v[24:27]
	v_mfma_f32_16x16x32_bf16 v[12:15], v[144:147], v[208:211], v[12:15]
	v_mfma_f32_16x16x32_bf16 v[8:11], v[160:163], v[208:211], v[8:11]
	v_mfma_f32_16x16x32_bf16 v[52:55], v[164:167], v[180:183], v[52:55]
	v_mfma_f32_16x16x32_bf16 v[48:51], v[172:175], v[180:183], v[48:51]
	v_mfma_f32_16x16x32_bf16 v[36:39], v[164:167], v[188:191], v[36:39]
	v_mfma_f32_16x16x32_bf16 v[32:35], v[172:175], v[188:191], v[32:35]
	v_mfma_f32_16x16x32_bf16 v[20:23], v[164:167], v[196:199], v[20:23]
	v_mfma_f32_16x16x32_bf16 v[16:19], v[172:175], v[196:199], v[16:19]
	v_mfma_f32_16x16x32_bf16 v[4:7], v[164:167], v[204:207], v[4:7]
	v_mfma_f32_16x16x32_bf16 v[0:3], v[172:175], v[204:207], v[0:3]
	v_mfma_f32_16x16x32_bf16 v[52:55], v[168:171], v[184:187], v[52:55]
	v_mfma_f32_16x16x32_bf16 v[48:51], v[176:179], v[184:187], v[48:51]
	v_mfma_f32_16x16x32_bf16 v[36:39], v[168:171], v[192:195], v[36:39]
	v_mfma_f32_16x16x32_bf16 v[32:35], v[176:179], v[192:195], v[32:35]
	v_mfma_f32_16x16x32_bf16 v[20:23], v[168:171], v[200:203], v[20:23]
	v_mfma_f32_16x16x32_bf16 v[16:19], v[176:179], v[200:203], v[16:19]
	v_mfma_f32_16x16x32_bf16 v[4:7], v[168:171], v[208:211], v[4:7]
	v_mfma_f32_16x16x32_bf16 v[0:3], v[176:179], v[208:211], v[0:3]
	s_setprio 0
	s_barrier
	s_add_i32 s25, 0, 0x18000
	v_add_u32_e32 v155, s25, v149
	s_add_i32 s61, 0, 0x1c000
	ds_read_b128 v[140:143], v155
	ds_read_b128 v[144:147], v155 offset:1024
	ds_read_b128 v[156:159], v155 offset:2048
	ds_read_b128 v[160:163], v155 offset:3072
	v_add_u32_e32 v155, s61, v149
	ds_read_b128 v[164:167], v155
	ds_read_b128 v[168:171], v155 offset:1024
	ds_read_b128 v[172:175], v155 offset:2048
	ds_read_b128 v[176:179], v155 offset:3072
	s_add_u32 s38, s38, 0x80000
	s_addc_u32 s39, s39, 0
	s_mov_b32 m0, s44
	v_lshl_add_u64 v[220:221], s[38:39], 0, v[134:135]
	ds_read_b128 v[180:183], v153 offset:32768
	ds_read_b128 v[184:187], v153 offset:33792
	ds_read_b128 v[188:191], v153 offset:34816
	ds_read_b128 v[192:195], v153 offset:35840
	ds_read_b128 v[196:199], v153 offset:36864
	ds_read_b128 v[200:203], v153 offset:37888
	ds_read_b128 v[204:207], v153 offset:38912
	ds_read_b128 v[208:211], v153 offset:39936
	global_load_lds_dwordx4 v[220:221], off
	v_lshl_add_u64 v[220:221], s[38:39], 0, v[130:131]
	s_mov_b32 m0, s45
	s_nop 0
	global_load_lds_dwordx4 v[220:221], off
	s_waitcnt vmcnt(8)
	s_waitcnt lgkmcnt(0)
	s_barrier
	s_setprio 1
	v_mfma_f32_16x16x32_bf16 v[124:127], v[140:143], v[180:183], v[124:127]
	v_mfma_f32_16x16x32_bf16 v[120:123], v[156:159], v[180:183], v[120:123]
	v_mfma_f32_16x16x32_bf16 v[108:111], v[140:143], v[188:191], v[108:111]
	v_mfma_f32_16x16x32_bf16 v[104:107], v[156:159], v[188:191], v[104:107]
	v_mfma_f32_16x16x32_bf16 v[92:95], v[140:143], v[196:199], v[92:95]
	v_mfma_f32_16x16x32_bf16 v[88:91], v[156:159], v[196:199], v[88:91]
	v_mfma_f32_16x16x32_bf16 v[76:79], v[140:143], v[204:207], v[76:79]
	v_mfma_f32_16x16x32_bf16 v[72:75], v[156:159], v[204:207], v[72:75]
	v_mfma_f32_16x16x32_bf16 v[124:127], v[144:147], v[184:187], v[124:127]
	v_mfma_f32_16x16x32_bf16 v[120:123], v[160:163], v[184:187], v[120:123]
	v_mfma_f32_16x16x32_bf16 v[108:111], v[144:147], v[192:195], v[108:111]
	v_mfma_f32_16x16x32_bf16 v[104:107], v[160:163], v[192:195], v[104:107]
	v_mfma_f32_16x16x32_bf16 v[92:95], v[144:147], v[200:203], v[92:95]
	v_mfma_f32_16x16x32_bf16 v[88:91], v[160:163], v[200:203], v[88:91]
	v_mfma_f32_16x16x32_bf16 v[76:79], v[144:147], v[208:211], v[76:79]
	v_mfma_f32_16x16x32_bf16 v[72:75], v[160:163], v[208:211], v[72:75]
	v_mfma_f32_16x16x32_bf16 v[116:119], v[164:167], v[180:183], v[116:119]
	v_mfma_f32_16x16x32_bf16 v[112:115], v[172:175], v[180:183], v[112:115]
	v_mfma_f32_16x16x32_bf16 v[100:103], v[164:167], v[188:191], v[100:103]
	v_mfma_f32_16x16x32_bf16 v[96:99], v[172:175], v[188:191], v[96:99]
	v_mfma_f32_16x16x32_bf16 v[84:87], v[164:167], v[196:199], v[84:87]
	v_mfma_f32_16x16x32_bf16 v[80:83], v[172:175], v[196:199], v[80:83]
	v_mfma_f32_16x16x32_bf16 v[68:71], v[164:167], v[204:207], v[68:71]
	v_mfma_f32_16x16x32_bf16 v[64:67], v[172:175], v[204:207], v[64:67]
	v_mfma_f32_16x16x32_bf16 v[116:119], v[168:171], v[184:187], v[116:119]
	v_mfma_f32_16x16x32_bf16 v[112:115], v[176:179], v[184:187], v[112:115]
	v_mfma_f32_16x16x32_bf16 v[100:103], v[168:171], v[192:195], v[100:103]
	v_mfma_f32_16x16x32_bf16 v[96:99], v[176:179], v[192:195], v[96:99]
	v_mfma_f32_16x16x32_bf16 v[84:87], v[168:171], v[200:203], v[84:87]
	v_mfma_f32_16x16x32_bf16 v[80:83], v[176:179], v[200:203], v[80:83]
	v_mfma_f32_16x16x32_bf16 v[68:71], v[168:171], v[208:211], v[68:71]
	v_mfma_f32_16x16x32_bf16 v[64:67], v[176:179], v[208:211], v[64:67]
	s_setprio 0
	s_barrier
; #define PG8_STAGE(bufoff, gbase, voff) do { _Pragma("unroll") for (int _i = 0; _i < 2; ++_i) \
;         __builtin_amdgcn_global_load_lds((const unsigned*)((const char*)(gbase) + (voff)[_i]), (LAS unsigned*)(lds + (bufoff) + ldsw + _i * 8192), 16, 0, 0); } while (0)
; #define PG8_LDA(dst, b, h) do { _Pragma("unroll") for (int m = 0; m < 4; ++m) _Pragma("unroll") for (int k = 0; k < 2; ++k) dst[m][k] = *(const LAS bf16x8*)(lds + PG8_SA(b, h) + aoff + m * 2048 + k * 1024); } while (0)
; #define PG8_MMA(ai, bj, At, Bt) do { __builtin_amdgcn_s_setprio(1); _Pragma("unroll") for (int m = 0; m < 4; ++m) _Pragma("unroll") for (int n = 0; n < 2; ++n) _Pragma("unroll") for (int k = 0; k < 2; ++k) \
;         acc[ai][bj][m][n] = __builtin_amdgcn_mfma_f32_16x16x32_bf16(Bt[n][k], At[m][k], acc[ai][bj][m][n], 0, 0, 0); __builtin_amdgcn_s_setprio(0); } while (0)
; #define PG8_WAIT_V(n) asm volatile("s_waitcnt vmcnt(" #n ")" ::: "memory")
; #define PG8_WAIT_L(n) asm volatile("s_waitcnt lgkmcnt(" #n ")" ::: "memory")
; #define PG8_BAR __builtin_amdgcn_s_barrier()
; #define PG8_SCHED __builtin_amdgcn_sched_barrier(0)
; template <class Epi, class Sched>
; __device__ __forceinline__ void gemm_phase(LAS unsigned char* lds, const int K, const Sched& S, const Epi& E) {
;     ...
;             PG8_LDA(At, 1, 1); PG8_STAGE(PG8_SB(1, 0), b3, voffB); PG8_STAGE(PG8_SB(1, 1), b3 + hstep, voffB); PG8_STAGE(PG8_SA(1, 0), a3, voffA);
;             PG8_WAIT_V(8); PG8_WAIT_L(0); PG8_BAR; PG8_MMA(1, 0, At, B0); PG8_MMA(1, 1, At, B1); PG8_BAR; PG8_SCHED;
;         }
;         if (wr == 0) PG8_BAR;
	s_add_i32 s25, s25, s40
	v_lshl_add_u64 v[212:213], v[212:213], 0, s[16:17]
	s_mov_b32 m0, s25
	ds_read_b128 v[180:183], v153 offset:49152
	ds_read_b128 v[184:187], v153 offset:50176
	ds_read_b128 v[188:191], v153 offset:51200
	ds_read_b128 v[192:195], v153 offset:52224
	ds_read_b128 v[196:199], v153 offset:53248
	ds_read_b128 v[200:203], v153 offset:54272
	ds_read_b128 v[204:207], v153 offset:55296
	ds_read_b128 v[208:211], v153 offset:56320
	global_load_lds_dwordx4 v[212:213], off
	s_add_i32 m0, s25, 0x2000
	s_add_u32 s36, s36, 0x80080
	v_lshl_add_u64 v[212:213], v[214:215], 0, s[16:17]
	s_addc_u32 s37, s37, 0
	s_add_i32 s25, s61, s40
	global_load_lds_dwordx4 v[212:213], off
	v_lshl_add_u64 v[212:213], s[36:37], 0, v[132:133]
	s_mov_b32 m0, s25
	s_nop 0
	global_load_lds_dwordx4 v[212:213], off
	v_lshl_add_u64 v[212:213], s[36:37], 0, v[128:129]
	s_add_i32 m0, s25, 0x2000
	s_nop 0
	global_load_lds_dwordx4 v[212:213], off
	v_lshl_add_u64 v[212:213], v[216:217], 0, s[16:17]
	s_mov_b32 m0, s47
	s_nop 0
	global_load_lds_dwordx4 v[212:213], off
	v_lshl_add_u64 v[212:213], v[218:219], 0, s[16:17]
	s_mov_b32 m0, s48
	s_nop 0
	global_load_lds_dwordx4 v[212:213], off
	s_waitcnt vmcnt(8)
	s_waitcnt lgkmcnt(0)
	s_barrier
	s_setprio 1
	v_mfma_f32_16x16x32_bf16 v[60:63], v[140:143], v[180:183], v[60:63]
	v_mfma_f32_16x16x32_bf16 v[56:59], v[156:159], v[180:183], v[56:59]
	v_mfma_f32_16x16x32_bf16 v[44:47], v[140:143], v[188:191], v[44:47]
	v_mfma_f32_16x16x32_bf16 v[40:43], v[156:159], v[188:191], v[40:43]
	v_mfma_f32_16x16x32_bf16 v[28:31], v[140:143], v[196:199], v[28:31]
	v_mfma_f32_16x16x32_bf16 v[24:27], v[156:159], v[196:199], v[24:27]
	v_mfma_f32_16x16x32_bf16 v[12:15], v[140:143], v[204:207], v[12:15]
	v_mfma_f32_16x16x32_bf16 v[8:11], v[156:159], v[204:207], v[8:11]
	v_mfma_f32_16x16x32_bf16 v[60:63], v[144:147], v[184:187], v[60:63]
	v_mfma_f32_16x16x32_bf16 v[56:59], v[160:163], v[184:187], v[56:59]
	v_mfma_f32_16x16x32_bf16 v[44:47], v[144:147], v[192:195], v[44:47]
	v_mfma_f32_16x16x32_bf16 v[40:43], v[160:163], v[192:195], v[40:43]
	v_mfma_f32_16x16x32_bf16 v[28:31], v[144:147], v[200:203], v[28:31]
	v_mfma_f32_16x16x32_bf16 v[24:27], v[160:163], v[200:203], v[24:27]
	v_mfma_f32_16x16x32_bf16 v[12:15], v[144:147], v[208:211], v[12:15]
	v_mfma_f32_16x16x32_bf16 v[8:11], v[160:163], v[208:211], v[8:11]
	v_mfma_f32_16x16x32_bf16 v[52:55], v[164:167], v[180:183], v[52:55]
	v_mfma_f32_16x16x32_bf16 v[48:51], v[172:175], v[180:183], v[48:51]
	v_mfma_f32_16x16x32_bf16 v[36:39], v[164:167], v[188:191], v[36:39]
	v_mfma_f32_16x16x32_bf16 v[32:35], v[172:175], v[188:191], v[32:35]
	v_mfma_f32_16x16x32_bf16 v[20:23], v[164:167], v[196:199], v[20:23]
	v_mfma_f32_16x16x32_bf16 v[16:19], v[172:175], v[196:199], v[16:19]
	v_mfma_f32_16x16x32_bf16 v[4:7], v[164:167], v[204:207], v[4:7]
	v_mfma_f32_16x16x32_bf16 v[0:3], v[172:175], v[204:207], v[0:3]
	v_mfma_f32_16x16x32_bf16 v[52:55], v[168:171], v[184:187], v[52:55]
	v_mfma_f32_16x16x32_bf16 v[48:51], v[176:179], v[184:187], v[48:51]
	v_mfma_f32_16x16x32_bf16 v[36:39], v[168:171], v[192:195], v[36:39]
	v_mfma_f32_16x16x32_bf16 v[32:35], v[176:179], v[192:195], v[32:35]
	v_mfma_f32_16x16x32_bf16 v[20:23], v[168:171], v[200:203], v[20:23]
	v_mfma_f32_16x16x32_bf16 v[16:19], v[176:179], v[200:203], v[16:19]
	v_mfma_f32_16x16x32_bf16 v[4:7], v[168:171], v[208:211], v[4:7]
	v_mfma_f32_16x16x32_bf16 v[0:3], v[176:179], v[208:211], v[0:3]
	s_setprio 0
	s_barrier
	s_add_i32 s23, s23, 2
	s_add_u32 s34, s34, 0x100
	s_addc_u32 s35, s35, 0
	s_add_u32 s8, s8, 0x100
	s_addc_u32 s9, s9, 0
	s_cmp_gt_u32 s23, 29
	s_cbranch_scc0 .LBB0_1433
	s_and_b64 vcc, exec, s[18:19]
	s_cbranch_vccz .LBB0_1436
	s_barrier

; #define PG8_STAGE(bufoff, gbase, voff) do { _Pragma("unroll") for (int _i = 0; _i < 2; ++_i) \
;         __builtin_amdgcn_global_load_lds((const unsigned*)((const char*)(gbase) + (voff)[_i]), (LAS unsigned*)(lds + (bufoff) + ldsw + _i * 8192), 16, 0, 0); } while (0)
; #define PG8_LDA(dst, b, h) do { _Pragma("unroll") for (int m = 0; m < 4; ++m) _Pragma("unroll") for (int k = 0; k < 2; ++k) dst[m][k] = *(const LAS bf16x8*)(lds + PG8_SA(b, h) + aoff + m * 2048 + k * 1024); } while (0)
; #define PG8_LDB(dst, b, h) do { _Pragma("unroll") for (int n = 0; n < 2; ++n) _Pragma("unroll") for (int k = 0; k < 2; ++k) dst[n][k] = *(const LAS bf16x8*)(lds + PG8_SB(b, h) + boff + n * 2048 + k * 1024); } while (0)
; #define PG8_MMA(ai, bj, At, Bt) do { __builtin_amdgcn_s_setprio(1); _Pragma("unroll") for (int m = 0; m < 4; ++m) _Pragma("unroll") for (int n = 0; n < 2; ++n) _Pragma("unroll") for (int k = 0; k < 2; ++k) \
;         acc[ai][bj][m][n] = __builtin_amdgcn_mfma_f32_16x16x32_bf16(Bt[n][k], At[m][k], acc[ai][bj][m][n], 0, 0, 0); __builtin_amdgcn_s_setprio(0); } while (0)
; #define PG8_WAIT_V(n) asm volatile("s_waitcnt vmcnt(" #n ")" ::: "memory")
; #define PG8_WAIT_L(n) asm volatile("s_waitcnt lgkmcnt(" #n ")" ::: "memory")
; #define PG8_BAR __builtin_amdgcn_s_barrier()
; #define PG8_SCHED __builtin_amdgcn_sched_barrier(0)
; template <class Epi, class Sched>
; __device__ __forceinline__ void gemm_phase(LAS unsigned char* lds, const int K, const Sched& S, const Epi& E) {
;     ...
;         for (int t = 0; t < nt; t += 2) {
;             const bool last = (t == nt - 2);
;             const char* a1 = cA + (size_t)(t + 1) * kstep;
;             const char* a2 = last ? nA : cA + (size_t)(t + 2) * kstep; const char* b2 = last ? nB : cB + (size_t)(t + 2) * kstep;
;             const char* a3 = a2 + kstep; const char* b3 = b2 + kstep;
;             PG8_LDB(B0, 0, 0); PG8_LDB(B1, 0, 1); PG8_SCHED; PG8_LDA(At, 0, 0); PG8_STAGE(PG8_SA(1, 1), a1 + hstep, voffA);
;             PG8_WAIT_V(8); PG8_WAIT_L(0); PG8_BAR; PG8_MMA(0, 0, At, B0); PG8_MMA(0, 1, At, B1); PG8_BAR; PG8_SCHED;
;             PG8_LDA(At, 0, 1); PG8_STAGE(PG8_SB(0, 0), b2, voffB); PG8_STAGE(PG8_SB(0, 1), b2 + hstep, voffB); PG8_STAGE(PG8_SA(0, 0), a2, voffA);
;             PG8_WAIT_V(8); PG8_WAIT_L(0); PG8_BAR; PG8_MMA(1, 0, At, B0); PG8_MMA(1, 1, At, B1); PG8_BAR; PG8_SCHED;
.LBB0_1513:
	ds_read_b128 v[140:143], v147
	ds_read_b128 v[152:155], v147 offset:1024
	ds_read_b128 v[156:159], v147 offset:2048
	ds_read_b128 v[160:163], v147 offset:3072
	ds_read_b128 v[164:167], v148
	ds_read_b128 v[168:171], v148 offset:1024
	ds_read_b128 v[172:175], v148 offset:2048
	ds_read_b128 v[176:179], v148 offset:3072
	s_add_u32 s24, s22, 0xffea0080
	s_addc_u32 s25, s23, -1
	s_cmpk_eq_i32 s61, 0x54
	s_cselect_b32 s27, s17, s25
	s_cselect_b32 s26, s16, s24
	s_cselect_b32 s25, s19, s9
	s_cselect_b32 s24, s18, s8
	s_mov_b32 m0, s45
	v_lshl_add_u64 v[212:213], s[22:23], 0, v[136:137]
	ds_read_b128 v[180:183], v149
	ds_read_b128 v[184:187], v149 offset:1024
	ds_read_b128 v[188:191], v149 offset:2048
	ds_read_b128 v[192:195], v149 offset:3072
	ds_read_b128 v[196:199], v149 offset:4096
	ds_read_b128 v[200:203], v149 offset:5120
	ds_read_b128 v[204:207], v149 offset:6144
	ds_read_b128 v[208:211], v149 offset:7168
	global_load_lds_dwordx4 v[212:213], off
	v_lshl_add_u64 v[212:213], s[22:23], 0, v[138:139]
	s_mov_b32 m0, s46
	s_nop 0
	global_load_lds_dwordx4 v[212:213], off
	s_waitcnt vmcnt(8)
	s_waitcnt lgkmcnt(0)
	s_barrier
	s_setprio 1
	v_mfma_f32_16x16x32_bf16 v[124:127], v[140:143], v[180:183], v[124:127]
	v_mfma_f32_16x16x32_bf16 v[120:123], v[156:159], v[180:183], v[120:123]
	v_mfma_f32_16x16x32_bf16 v[108:111], v[140:143], v[188:191], v[108:111]
	v_mfma_f32_16x16x32_bf16 v[104:107], v[156:159], v[188:191], v[104:107]
	v_mfma_f32_16x16x32_bf16 v[92:95], v[140:143], v[196:199], v[92:95]
	v_mfma_f32_16x16x32_bf16 v[88:91], v[156:159], v[196:199], v[88:91]
	v_mfma_f32_16x16x32_bf16 v[76:79], v[140:143], v[204:207], v[76:79]
	v_mfma_f32_16x16x32_bf16 v[72:75], v[156:159], v[204:207], v[72:75]
	v_mfma_f32_16x16x32_bf16 v[124:127], v[152:155], v[184:187], v[124:127]
	v_mfma_f32_16x16x32_bf16 v[120:123], v[160:163], v[184:187], v[120:123]
	v_mfma_f32_16x16x32_bf16 v[108:111], v[152:155], v[192:195], v[108:111]
	v_mfma_f32_16x16x32_bf16 v[104:107], v[160:163], v[192:195], v[104:107]
	v_mfma_f32_16x16x32_bf16 v[92:95], v[152:155], v[200:203], v[92:95]
	v_mfma_f32_16x16x32_bf16 v[88:91], v[160:163], v[200:203], v[88:91]
	v_mfma_f32_16x16x32_bf16 v[76:79], v[152:155], v[208:211], v[76:79]
	v_mfma_f32_16x16x32_bf16 v[72:75], v[160:163], v[208:211], v[72:75]
	v_mfma_f32_16x16x32_bf16 v[116:119], v[164:167], v[180:183], v[116:119]
	v_mfma_f32_16x16x32_bf16 v[112:115], v[172:175], v[180:183], v[112:115]
	v_mfma_f32_16x16x32_bf16 v[100:103], v[164:167], v[188:191], v[100:103]
	v_mfma_f32_16x16x32_bf16 v[96:99], v[172:175], v[188:191], v[96:99]
	v_mfma_f32_16x16x32_bf16 v[84:87], v[164:167], v[196:199], v[84:87]
	v_mfma_f32_16x16x32_bf16 v[80:83], v[172:175], v[196:199], v[80:83]
	v_mfma_f32_16x16x32_bf16 v[68:71], v[164:167], v[204:207], v[68:71]
	v_mfma_f32_16x16x32_bf16 v[64:67], v[172:175], v[204:207], v[64:67]
	v_mfma_f32_16x16x32_bf16 v[116:119], v[168:171], v[184:187], v[116:119]
	v_mfma_f32_16x16x32_bf16 v[112:115], v[176:179], v[184:187], v[112:115]
	v_mfma_f32_16x16x32_bf16 v[100:103], v[168:171], v[192:195], v[100:103]
	v_mfma_f32_16x16x32_bf16 v[96:99], v[176:179], v[192:195], v[96:99]
	v_mfma_f32_16x16x32_bf16 v[84:87], v[168:171], v[200:203], v[84:87]
	v_mfma_f32_16x16x32_bf16 v[80:83], v[176:179], v[200:203], v[80:83]
	v_mfma_f32_16x16x32_bf16 v[68:71], v[168:171], v[208:211], v[68:71]
	v_mfma_f32_16x16x32_bf16 v[64:67], v[176:179], v[208:211], v[64:67]
	s_setprio 0
	s_barrier
	s_mov_b32 m0, s47
	v_lshl_add_u64 v[212:213], s[24:25], 0, v[130:131]
	s_add_u32 s62, s24, 0x160000
	ds_read_b128 v[180:183], v149 offset:16384
	ds_read_b128 v[184:187], v149 offset:17408
	ds_read_b128 v[188:191], v149 offset:18432
	ds_read_b128 v[192:195], v149 offset:19456
	ds_read_b128 v[196:199], v149 offset:20480
	ds_read_b128 v[200:203], v149 offset:21504
	ds_read_b128 v[204:207], v149 offset:22528
	ds_read_b128 v[208:211], v149 offset:23552
	global_load_lds_dwordx4 v[212:213], off
	v_lshl_add_u64 v[214:215], s[24:25], 0, v[134:135]
	s_mov_b32 m0, s48
	s_addc_u32 s63, s25, 0
	s_add_i32 s64, s44, s34
	global_load_lds_dwordx4 v[214:215], off
	v_lshl_add_u64 v[216:217], s[62:63], 0, v[130:131]
	s_mov_b32 m0, s64
	v_lshl_add_u64 v[218:219], s[26:27], 0, v[132:133]
	global_load_lds_dwordx4 v[216:217], off
	v_lshl_add_u64 v[216:217], s[62:63], 0, v[134:135]
	s_add_i32 m0, s64, 0x2000
	s_nop 0
	global_load_lds_dwordx4 v[216:217], off
	v_lshl_add_u64 v[216:217], s[26:27], 0, v[128:129]
	s_mov_b32 m0, s35
	s_nop 0
	global_load_lds_dwordx4 v[216:217], off
	s_mov_b32 m0, s36
	s_nop 0
	global_load_lds_dwordx4 v[218:219], off
	s_waitcnt vmcnt(8)
	s_waitcnt lgkmcnt(0)
	s_barrier
; #define PG8_STAGE(bufoff, gbase, voff) do { _Pragma("unroll") for (int _i = 0; _i < 2; ++_i) \
;         __builtin_amdgcn_global_load_lds((const unsigned*)((const char*)(gbase) + (voff)[_i]), (LAS unsigned*)(lds + (bufoff) + ldsw + _i * 8192), 16, 0, 0); } while (0)
; #define PG8_LDA(dst, b, h) do { _Pragma("unroll") for (int m = 0; m < 4; ++m) _Pragma("unroll") for (int k = 0; k < 2; ++k) dst[m][k] = *(const LAS bf16x8*)(lds + PG8_SA(b, h) + aoff + m * 2048 + k * 1024); } while (0)
; #define PG8_LDB(dst, b, h) do { _Pragma("unroll") for (int n = 0; n < 2; ++n) _Pragma("unroll") for (int k = 0; k < 2; ++k) dst[n][k] = *(const LAS bf16x8*)(lds + PG8_SB(b, h) + boff + n * 2048 + k * 1024); } while (0)
; #define PG8_MMA(ai, bj, At, Bt) do { __builtin_amdgcn_s_setprio(1); _Pragma("unroll") for (int m = 0; m < 4; ++m) _Pragma("unroll") for (int n = 0; n < 2; ++n) _Pragma("unroll") for (int k = 0; k < 2; ++k) \
;         acc[ai][bj][m][n] = __builtin_amdgcn_mfma_f32_16x16x32_bf16(Bt[n][k], At[m][k], acc[ai][bj][m][n], 0, 0, 0); __builtin_amdgcn_s_setprio(0); } while (0)
; #define PG8_WAIT_V(n) asm volatile("s_waitcnt vmcnt(" #n ")" ::: "memory")
; #define PG8_WAIT_L(n) asm volatile("s_waitcnt lgkmcnt(" #n ")" ::: "memory")
; #define PG8_BAR __builtin_amdgcn_s_barrier()
; #define PG8_SCHED __builtin_amdgcn_sched_barrier(0)
; template <class Epi, class Sched>
; __device__ __forceinline__ void gemm_phase(LAS unsigned char* lds, const int K, const Sched& S, const Epi& E) {
;     ...
;             PG8_WAIT_V(8); PG8_WAIT_L(0); PG8_BAR; PG8_MMA(1, 0, At, B0); PG8_MMA(1, 1, At, B1); PG8_BAR; PG8_SCHED;
;             PG8_LDB(B0, 1, 0); PG8_LDB(B1, 1, 1); PG8_SCHED; PG8_LDA(At, 1, 0); PG8_STAGE(PG8_SA(0, 1), a2 + hstep, voffA);
;             PG8_WAIT_V(8); PG8_WAIT_L(0); PG8_BAR; PG8_MMA(0, 0, At, B0); PG8_MMA(0, 1, At, B1); PG8_BAR; PG8_SCHED;
	s_setprio 1
	v_mfma_f32_16x16x32_bf16 v[60:63], v[140:143], v[180:183], v[60:63]
	v_mfma_f32_16x16x32_bf16 v[56:59], v[156:159], v[180:183], v[56:59]
	v_mfma_f32_16x16x32_bf16 v[44:47], v[140:143], v[188:191], v[44:47]
	v_mfma_f32_16x16x32_bf16 v[40:43], v[156:159], v[188:191], v[40:43]
	v_mfma_f32_16x16x32_bf16 v[28:31], v[140:143], v[196:199], v[28:31]
	v_mfma_f32_16x16x32_bf16 v[24:27], v[156:159], v[196:199], v[24:27]
	v_mfma_f32_16x16x32_bf16 v[12:15], v[140:143], v[204:207], v[12:15]
	v_mfma_f32_16x16x32_bf16 v[8:11], v[156:159], v[204:207], v[8:11]
	v_mfma_f32_16x16x32_bf16 v[60:63], v[152:155], v[184:187], v[60:63]
	v_mfma_f32_16x16x32_bf16 v[56:59], v[160:163], v[184:187], v[56:59]
	v_mfma_f32_16x16x32_bf16 v[44:47], v[152:155], v[192:195], v[44:47]
	v_mfma_f32_16x16x32_bf16 v[40:43], v[160:163], v[192:195], v[40:43]
	v_mfma_f32_16x16x32_bf16 v[28:31], v[152:155], v[200:203], v[28:31]
	v_mfma_f32_16x16x32_bf16 v[24:27], v[160:163], v[200:203], v[24:27]
	v_mfma_f32_16x16x32_bf16 v[12:15], v[152:155], v[208:211], v[12:15]
	v_mfma_f32_16x16x32_bf16 v[8:11], v[160:163], v[208:211], v[8:11]
	v_mfma_f32_16x16x32_bf16 v[52:55], v[164:167], v[180:183], v[52:55]
	v_mfma_f32_16x16x32_bf16 v[48:51], v[172:175], v[180:183], v[48:51]
	v_mfma_f32_16x16x32_bf16 v[36:39], v[164:167], v[188:191], v[36:39]
	v_mfma_f32_16x16x32_bf16 v[32:35], v[172:175], v[188:191], v[32:35]
	v_mfma_f32_16x16x32_bf16 v[20:23], v[164:167], v[196:199], v[20:23]
	v_mfma_f32_16x16x32_bf16 v[16:19], v[172:175], v[196:199], v[16:19]
	v_mfma_f32_16x16x32_bf16 v[4:7], v[164:167], v[204:207], v[4:7]
	v_mfma_f32_16x16x32_bf16 v[0:3], v[172:175], v[204:207], v[0:3]
	v_mfma_f32_16x16x32_bf16 v[52:55], v[168:171], v[184:187], v[52:55]
	v_mfma_f32_16x16x32_bf16 v[48:51], v[176:179], v[184:187], v[48:51]
	v_mfma_f32_16x16x32_bf16 v[36:39], v[168:171], v[192:195], v[36:39]
	v_mfma_f32_16x16x32_bf16 v[32:35], v[176:179], v[192:195], v[32:35]
	v_mfma_f32_16x16x32_bf16 v[20:23], v[168:171], v[200:203], v[20:23]
	v_mfma_f32_16x16x32_bf16 v[16:19], v[176:179], v[200:203], v[16:19]
	v_mfma_f32_16x16x32_bf16 v[4:7], v[168:171], v[208:211], v[4:7]
	v_mfma_f32_16x16x32_bf16 v[0:3], v[176:179], v[208:211], v[0:3]
	s_setprio 0
	s_barrier
	s_add_i32 s62, 0, 0x18000
	v_add_u32_e32 v151, s62, v146
	s_add_i32 s63, 0, 0x1c000
	ds_read_b128 v[140:143], v151
	ds_read_b128 v[152:155], v151 offset:1024
	ds_read_b128 v[156:159], v151 offset:2048
	ds_read_b128 v[160:163], v151 offset:3072
	v_add_u32_e32 v151, s63, v146
	ds_read_b128 v[164:167], v151
	ds_read_b128 v[168:171], v151 offset:1024
	ds_read_b128 v[172:175], v151 offset:2048
	ds_read_b128 v[176:179], v151 offset:3072
	s_add_u32 s26, s26, 0x160000
	s_addc_u32 s27, s27, 0
	s_mov_b32 m0, s37
	v_lshl_add_u64 v[220:221], s[26:27], 0, v[128:129]
	ds_read_b128 v[180:183], v149 offset:32768
	ds_read_b128 v[184:187], v149 offset:33792
	ds_read_b128 v[188:191], v149 offset:34816
	ds_read_b128 v[192:195], v149 offset:35840
	ds_read_b128 v[196:199], v149 offset:36864
	ds_read_b128 v[200:203], v149 offset:37888
	ds_read_b128 v[204:207], v149 offset:38912
	ds_read_b128 v[208:211], v149 offset:39936
	global_load_lds_dwordx4 v[220:221], off
	v_lshl_add_u64 v[220:221], s[26:27], 0, v[132:133]
	s_mov_b32 m0, s38
	s_nop 0
	global_load_lds_dwordx4 v[220:221], off
	s_waitcnt vmcnt(8)
	s_waitcnt lgkmcnt(0)
	s_barrier
	s_setprio 1
	v_mfma_f32_16x16x32_bf16 v[124:127], v[140:143], v[180:183], v[124:127]
	v_mfma_f32_16x16x32_bf16 v[120:123], v[156:159], v[180:183], v[120:123]
	v_mfma_f32_16x16x32_bf16 v[108:111], v[140:143], v[188:191], v[108:111]
	v_mfma_f32_16x16x32_bf16 v[104:107], v[156:159], v[188:191], v[104:107]
	v_mfma_f32_16x16x32_bf16 v[92:95], v[140:143], v[196:199], v[92:95]
	v_mfma_f32_16x16x32_bf16 v[88:91], v[156:159], v[196:199], v[88:91]
	v_mfma_f32_16x16x32_bf16 v[76:79], v[140:143], v[204:207], v[76:79]
	v_mfma_f32_16x16x32_bf16 v[72:75], v[156:159], v[204:207], v[72:75]
	v_mfma_f32_16x16x32_bf16 v[124:127], v[152:155], v[184:187], v[124:127]
	v_mfma_f32_16x16x32_bf16 v[120:123], v[160:163], v[184:187], v[120:123]
	v_mfma_f32_16x16x32_bf16 v[108:111], v[152:155], v[192:195], v[108:111]
	v_mfma_f32_16x16x32_bf16 v[104:107], v[160:163], v[192:195], v[104:107]
	v_mfma_f32_16x16x32_bf16 v[92:95], v[152:155], v[200:203], v[92:95]
	v_mfma_f32_16x16x32_bf16 v[88:91], v[160:163], v[200:203], v[88:91]
	v_mfma_f32_16x16x32_bf16 v[76:79], v[152:155], v[208:211], v[76:79]
	v_mfma_f32_16x16x32_bf16 v[72:75], v[160:163], v[208:211], v[72:75]
	v_mfma_f32_16x16x32_bf16 v[116:119], v[164:167], v[180:183], v[116:119]
	v_mfma_f32_16x16x32_bf16 v[112:115], v[172:175], v[180:183], v[112:115]
	v_mfma_f32_16x16x32_bf16 v[100:103], v[164:167], v[188:191], v[100:103]
	v_mfma_f32_16x16x32_bf16 v[96:99], v[172:175], v[188:191], v[96:99]
	v_mfma_f32_16x16x32_bf16 v[84:87], v[164:167], v[196:199], v[84:87]
	v_mfma_f32_16x16x32_bf16 v[80:83], v[172:175], v[196:199], v[80:83]
	v_mfma_f32_16x16x32_bf16 v[68:71], v[164:167], v[204:207], v[68:71]
	v_mfma_f32_16x16x32_bf16 v[64:67], v[172:175], v[204:207], v[64:67]
	v_mfma_f32_16x16x32_bf16 v[116:119], v[168:171], v[184:187], v[116:119]
	v_mfma_f32_16x16x32_bf16 v[112:115], v[176:179], v[184:187], v[112:115]
	v_mfma_f32_16x16x32_bf16 v[100:103], v[168:171], v[192:195], v[100:103]
	v_mfma_f32_16x16x32_bf16 v[96:99], v[176:179], v[192:195], v[96:99]
	v_mfma_f32_16x16x32_bf16 v[84:87], v[168:171], v[200:203], v[84:87]
	v_mfma_f32_16x16x32_bf16 v[80:83], v[176:179], v[200:203], v[80:83]
	v_mfma_f32_16x16x32_bf16 v[68:71], v[168:171], v[208:211], v[68:71]
	v_mfma_f32_16x16x32_bf16 v[64:67], v[176:179], v[208:211], v[64:67]
	s_setprio 0
	s_barrier
; #define PG8_STAGE(bufoff, gbase, voff) do { _Pragma("unroll") for (int _i = 0; _i < 2; ++_i) \
;         __builtin_amdgcn_global_load_lds((const unsigned*)((const char*)(gbase) + (voff)[_i]), (LAS unsigned*)(lds + (bufoff) + ldsw + _i * 8192), 16, 0, 0); } while (0)
; #define PG8_LDA(dst, b, h) do { _Pragma("unroll") for (int m = 0; m < 4; ++m) _Pragma("unroll") for (int k = 0; k < 2; ++k) dst[m][k] = *(const LAS bf16x8*)(lds + PG8_SA(b, h) + aoff + m * 2048 + k * 1024); } while (0)
; #define PG8_MMA(ai, bj, At, Bt) do { __builtin_amdgcn_s_setprio(1); _Pragma("unroll") for (int m = 0; m < 4; ++m) _Pragma("unroll") for (int n = 0; n < 2; ++n) _Pragma("unroll") for (int k = 0; k < 2; ++k) \
;         acc[ai][bj][m][n] = __builtin_amdgcn_mfma_f32_16x16x32_bf16(Bt[n][k], At[m][k], acc[ai][bj][m][n], 0, 0, 0); __builtin_amdgcn_s_setprio(0); } while (0)
; #define PG8_WAIT_V(n) asm volatile("s_waitcnt vmcnt(" #n ")" ::: "memory")
; #define PG8_WAIT_L(n) asm volatile("s_waitcnt lgkmcnt(" #n ")" ::: "memory")
; #define PG8_BAR __builtin_amdgcn_s_barrier()
; #define PG8_SCHED __builtin_amdgcn_sched_barrier(0)
; template <class Epi, class Sched>
; __device__ __forceinline__ void gemm_phase(LAS unsigned char* lds, const int K, const Sched& S, const Epi& E) {
;     ...
;             PG8_LDA(At, 1, 1); PG8_STAGE(PG8_SB(1, 0), b3, voffB); PG8_STAGE(PG8_SB(1, 1), b3 + hstep, voffB); PG8_STAGE(PG8_SA(1, 0), a3, voffA);
;             PG8_WAIT_V(8); PG8_WAIT_L(0); PG8_BAR; PG8_MMA(1, 0, At, B0); PG8_MMA(1, 1, At, B1); PG8_BAR; PG8_SCHED;
;         }
;         if (wr == 0) PG8_BAR;
	s_add_i32 s26, s62, s34
	v_lshl_add_u64 v[212:213], v[212:213], 0, s[12:13]
	s_mov_b32 m0, s26
	ds_read_b128 v[180:183], v149 offset:49152
	ds_read_b128 v[184:187], v149 offset:50176
	ds_read_b128 v[188:191], v149 offset:51200
	ds_read_b128 v[192:195], v149 offset:52224
	ds_read_b128 v[196:199], v149 offset:53248
	ds_read_b128 v[200:203], v149 offset:54272
	ds_read_b128 v[204:207], v149 offset:55296
	ds_read_b128 v[208:211], v149 offset:56320
	global_load_lds_dwordx4 v[212:213], off
	s_add_i32 m0, s26, 0x2000
	s_add_u32 s24, s24, 0x160080
	v_lshl_add_u64 v[212:213], v[214:215], 0, s[12:13]
	s_addc_u32 s25, s25, 0
	s_add_i32 s26, s63, s34
	global_load_lds_dwordx4 v[212:213], off
	v_lshl_add_u64 v[212:213], s[24:25], 0, v[130:131]
	s_mov_b32 m0, s26
	s_nop 0
	global_load_lds_dwordx4 v[212:213], off
	v_lshl_add_u64 v[212:213], s[24:25], 0, v[134:135]
	s_add_i32 m0, s26, 0x2000
	s_nop 0
	global_load_lds_dwordx4 v[212:213], off
	v_lshl_add_u64 v[212:213], v[216:217], 0, s[12:13]
	s_mov_b32 m0, s42
	s_nop 0
	global_load_lds_dwordx4 v[212:213], off
	v_lshl_add_u64 v[212:213], v[218:219], 0, s[12:13]
	s_mov_b32 m0, s43
	s_nop 0
	global_load_lds_dwordx4 v[212:213], off
	s_waitcnt vmcnt(8)
	s_waitcnt lgkmcnt(0)
	s_barrier
	s_setprio 1
	v_mfma_f32_16x16x32_bf16 v[60:63], v[140:143], v[180:183], v[60:63]
	v_mfma_f32_16x16x32_bf16 v[56:59], v[156:159], v[180:183], v[56:59]
	v_mfma_f32_16x16x32_bf16 v[44:47], v[140:143], v[188:191], v[44:47]
	v_mfma_f32_16x16x32_bf16 v[40:43], v[156:159], v[188:191], v[40:43]
	v_mfma_f32_16x16x32_bf16 v[28:31], v[140:143], v[196:199], v[28:31]
	v_mfma_f32_16x16x32_bf16 v[24:27], v[156:159], v[196:199], v[24:27]
	v_mfma_f32_16x16x32_bf16 v[12:15], v[140:143], v[204:207], v[12:15]
	v_mfma_f32_16x16x32_bf16 v[8:11], v[156:159], v[204:207], v[8:11]
	v_mfma_f32_16x16x32_bf16 v[60:63], v[152:155], v[184:187], v[60:63]
	v_mfma_f32_16x16x32_bf16 v[56:59], v[160:163], v[184:187], v[56:59]
	v_mfma_f32_16x16x32_bf16 v[44:47], v[152:155], v[192:195], v[44:47]
	v_mfma_f32_16x16x32_bf16 v[40:43], v[160:163], v[192:195], v[40:43]
	v_mfma_f32_16x16x32_bf16 v[28:31], v[152:155], v[200:203], v[28:31]
	v_mfma_f32_16x16x32_bf16 v[24:27], v[160:163], v[200:203], v[24:27]
	v_mfma_f32_16x16x32_bf16 v[12:15], v[152:155], v[208:211], v[12:15]
	v_mfma_f32_16x16x32_bf16 v[8:11], v[160:163], v[208:211], v[8:11]
	v_mfma_f32_16x16x32_bf16 v[52:55], v[164:167], v[180:183], v[52:55]
	v_mfma_f32_16x16x32_bf16 v[48:51], v[172:175], v[180:183], v[48:51]
	v_mfma_f32_16x16x32_bf16 v[36:39], v[164:167], v[188:191], v[36:39]
	v_mfma_f32_16x16x32_bf16 v[32:35], v[172:175], v[188:191], v[32:35]
	v_mfma_f32_16x16x32_bf16 v[20:23], v[164:167], v[196:199], v[20:23]
	v_mfma_f32_16x16x32_bf16 v[16:19], v[172:175], v[196:199], v[16:19]
	v_mfma_f32_16x16x32_bf16 v[4:7], v[164:167], v[204:207], v[4:7]
	v_mfma_f32_16x16x32_bf16 v[0:3], v[172:175], v[204:207], v[0:3]
	v_mfma_f32_16x16x32_bf16 v[52:55], v[168:171], v[184:187], v[52:55]
	v_mfma_f32_16x16x32_bf16 v[48:51], v[176:179], v[184:187], v[48:51]
	v_mfma_f32_16x16x32_bf16 v[36:39], v[168:171], v[192:195], v[36:39]
	v_mfma_f32_16x16x32_bf16 v[32:35], v[176:179], v[192:195], v[32:35]
	v_mfma_f32_16x16x32_bf16 v[20:23], v[168:171], v[200:203], v[20:23]
	v_mfma_f32_16x16x32_bf16 v[16:19], v[176:179], v[200:203], v[16:19]
	v_mfma_f32_16x16x32_bf16 v[4:7], v[168:171], v[208:211], v[4:7]
	v_mfma_f32_16x16x32_bf16 v[0:3], v[176:179], v[208:211], v[0:3]
	s_setprio 0
	s_barrier
	s_add_i32 s61, s61, 2
	s_add_u32 s22, s22, 0x100
	s_addc_u32 s23, s23, 0
	s_add_u32 s8, s8, 0x100
	s_addc_u32 s9, s9, 0
	s_cmpk_gt_u32 s61, 0x55
	s_cbranch_scc0 .LBB0_1513
	s_and_b64 vcc, exec, s[14:15]
	s_cbranch_vccz .LBB0_1516
	s_barrier
